# EpiRes MODE0 epilogues (4 GEMM phases): residual row loads ring-prefetched 5 rows ahead into free fragment regs, counted vmcnt waits so no wait covers atomics/stores
# speedup vs baseline: 1.0020x; 1.0020x over previous
; __device__ __forceinline__ float ss_scale(const u64* ss, int row) { return __builtin_amdgcn_rsqf((float)ss[row] * (1.f / 4294967296.f / 1024.f) + EPS); }
; __device__ __forceinline__ u64 ss_fix(float q) { return (u64)(q * 4294967296.f); }
;     __device__ __forceinline__ void operator()(const f32x4 (&acc)[2][2][4][2], const pg8::Unit& u, int wr, int wc, int fr, int fq) const {
;     ...
; #pragma unroll
;         for (int ai = 0; ai < 2; ++ai)
; #pragma unroll
;             for (int m = 0; m < 4; ++m) {
;                 const int row = row0 + ai * 128 + m * 16;
;                 float q = 0.f, qw = 0.f, sh = 1.f;
;                 if constexpr (MODE == 2) sh = ss_scale(rss, row);
; #pragma unroll
;                 for (int bj = 0; bj < 2; ++bj) {
;                     const int c = col0 + bj * 128;
;                     const u32x4 rb = *(const u32x4*)(hb + (size_t)row * DM + c);
;                     f32x4 r0 = {bflo(rb.x), bfhi(rb.x), bflo(rb.y), bfhi(rb.y)}, r1 = {bflo(rb.z), bfhi(rb.z), bflo(rb.w), bfhi(rb.w)};
;                     if constexpr (MODE == 2) { r0 = r0 * sh * g0[bj]; r1 = r1 * sh * g1[bj]; }
;                     const f32x4 v0 = r0 + acc[ai][bj][m][0], v1 = r1 + acc[ai][bj][m][1];
;                     if constexpr (WF32) { *(f32x4*)(out + (size_t)row * DM + c) = v0; *(f32x4*)(out + (size_t)row * DM + c + 4) = v1; }
;                     u32x4 w; w.x = pkbf(v0[0], v0[1]); w.y = pkbf(v0[2], v0[3]); w.z = pkbf(v1[0], v1[1]); w.w = pkbf(v1[2], v1[3]);
;                     *(u32x4*)(hb + (size_t)row * DM + c) = w;
;                     const f32x4 s0 = v0 * v0, s1 = v1 * v1;
;                     q += (s0[0] + s0[1]) + (s0[2] + s0[3]) + (s1[0] + s1[1]) + (s1[2] + s1[3]);
;                     if constexpr (MODE == 1) { const f32x4 t0 = s0 * g0[bj], t1 = s1 * g1[bj]; qw += (t0[0] + t0[1]) + (t0[2] + t0[3]) + (t1[0] + t1[1]) + (t1[2] + t1[3]); }
;                 }
;                 q += __shfl_xor(q, 16); q += __shfl_xor(q, 32);
;                 if constexpr (MODE == 1) { qw += __shfl_xor(qw, 16); qw += __shfl_xor(qw, 32); }
;                 if (fq == 0) {
;                     __hip_atomic_fetch_add(ssn + row, ss_fix(q), __ATOMIC_RELAXED, __HIP_MEMORY_SCOPE_AGENT);
;                     if constexpr (MODE == 1) __hip_atomic_fetch_add(ssw + row, ss_fix(qw), __ATOMIC_RELAXED, __HIP_MEMORY_SCOPE_AGENT);
;                 }
;             }
.LBB0_358:
	v_lshl_add_u32 v146, s56, 8, v148
	v_ashrrev_i32_e32 v147, 31, v146
	v_lshl_or_b32 v144, s55, 8, v149
	v_lshlrev_b64 v[156:157], 11, v[146:147]
	v_lshl_add_u64 v[156:157], s[10:11], 0, v[156:157]
	v_ashrrev_i32_e32 v145, 31, v144
	v_lshl_add_u64 v[166:167], v[144:145], 1, v[156:157]
	global_load_dwordx4 v[158:161], v[166:167], off
	global_load_dwordx4 v[162:165], v[166:167], off offset:256
	v_mov_b32_e32 v220, v166
	v_mov_b32_e32 v221, v167
	s_mov_b32 s100, 0x8000
	s_mov_b32 s101, 0
	v_lshl_add_u64 v[222:223], v[166:167], 0, s[100:101]
	global_load_dwordx4 v[184:187], v[222:223], off
	global_load_dwordx4 v[188:191], v[222:223], off offset:256
	s_mov_b32 s100, 0x10000
	s_mov_b32 s101, 0
	v_lshl_add_u64 v[222:223], v[166:167], 0, s[100:101]
	global_load_dwordx4 v[192:195], v[222:223], off
	global_load_dwordx4 v[200:203], v[222:223], off offset:256
	s_mov_b32 s100, 0x18000
	s_mov_b32 s101, 0
	v_lshl_add_u64 v[222:223], v[166:167], 0, s[100:101]
	global_load_dwordx4 v[204:207], v[222:223], off
	global_load_dwordx4 v[208:211], v[222:223], off offset:256
	s_mov_b32 s100, 0x40000
	s_mov_b32 s101, 0
	v_lshl_add_u64 v[222:223], v[166:167], 0, s[100:101]
	global_load_dwordx4 v[212:215], v[222:223], off
	global_load_dwordx4 v[216:219], v[222:223], off offset:256
	s_mov_b32 s100, 0x48000
	s_mov_b32 s101, 0
	v_lshl_add_u64 v[222:223], v[166:167], 0, s[100:101]
	global_load_dwordx4 v[176:179], v[222:223], off
	global_load_dwordx4 v[180:183], v[222:223], off offset:256
	v_and_b32_e32 v157, 64, v155
	v_xor_b32_e32 v156, 16, v155
	v_add_u32_e32 v157, 64, v157
	v_xor_b32_e32 v168, 32, v155
	v_cmp_lt_i32_e32 vcc, v156, v157
	s_waitcnt vmcnt(10)
	v_and_b32_e32 v169, 0xffff0000, v158
	v_cndmask_b32_e32 v156, v155, v156, vcc
	v_cmp_lt_i32_e32 vcc, v168, v157
	v_lshlrev_b32_e32 v157, 2, v156
	v_lshlrev_b32_e32 v170, 16, v160
	v_cndmask_b32_e32 v168, v155, v168, vcc
	v_lshlrev_b32_e32 v156, 2, v168
	v_lshlrev_b32_e32 v168, 16, v158
	v_lshlrev_b32_e32 v158, 16, v159
	v_and_b32_e32 v159, 0xffff0000, v159
	v_and_b32_e32 v171, 0xffff0000, v160
	v_lshlrev_b32_e32 v160, 16, v161
	v_and_b32_e32 v161, 0xffff0000, v161
	v_lshlrev_b32_e32 v172, 16, v162
	v_and_b32_e32 v173, 0xffff0000, v162
	v_lshlrev_b32_e32 v162, 16, v163
	v_and_b32_e32 v163, 0xffff0000, v163
	v_lshlrev_b32_e32 v174, 16, v164
	v_and_b32_e32 v175, 0xffff0000, v164
	v_lshlrev_b32_e32 v164, 16, v165
	v_and_b32_e32 v165, 0xffff0000, v165
	v_pk_add_f32 v[126:127], v[126:127], v[158:159]
	v_pk_add_f32 v[124:125], v[124:125], v[168:169]
	v_pk_add_f32 v[122:123], v[122:123], v[160:161]
	v_pk_add_f32 v[118:119], v[118:119], v[162:163]
	v_pk_add_f32 v[116:117], v[116:117], v[172:173]
	v_pk_add_f32 v[120:121], v[120:121], v[170:171]
	v_pk_add_f32 v[158:159], v[114:115], v[164:165]
	v_pk_add_f32 v[160:161], v[112:113], v[174:175]
	v_cvt_pk_bf16_f32 v112, v124, v125
	v_cvt_pk_bf16_f32 v113, v126, v127
	v_pk_mul_f32 v[114:115], v[126:127], v[126:127]
	v_pk_mul_f32 v[124:125], v[124:125], v[124:125]
	v_pk_mul_f32 v[126:127], v[122:123], v[122:123]
	v_pk_mul_f32 v[164:165], v[118:119], v[118:119]
	v_pk_mul_f32 v[168:169], v[116:117], v[116:117]
	v_pk_mul_f32 v[162:163], v[120:121], v[120:121]
	v_pk_mul_f32 v[172:173], v[160:161], v[160:161]
	v_add_f32_e32 v124, v124, v125
	v_add_f32_e32 v114, v114, v115
	v_add_f32_e32 v125, v126, v127
	v_add_f32_e32 v126, v168, v169
	v_add_f32_e32 v127, v164, v165
	v_pk_mul_f32 v[170:171], v[158:159], v[158:159]
	v_add_f32_e32 v115, v162, v163
	v_add_f32_e32 v162, v172, v173
	v_add_f32_e32 v114, v124, v114
	v_add_f32_e32 v124, v126, v127
	v_add_f32_e32 v163, v170, v171
	v_add_f32_e32 v114, v115, v114
	v_add_f32_e32 v115, v162, v124
	v_add_f32_e32 v114, v125, v114
	v_add_f32_e32 v115, v163, v115
	v_add_f32_e32 v124, v114, v115
	ds_bpermute_b32 v125, v157, v124
	v_cvt_pk_bf16_f32 v114, v120, v121
	v_cvt_pk_bf16_f32 v115, v122, v123
	global_store_dwordx4 v[166:167], v[112:115], off
	s_waitcnt lgkmcnt(0)
	s_nop 0
	v_add_f32_e32 v112, v124, v125
	ds_bpermute_b32 v113, v156, v112
	v_cvt_pk_bf16_f32 v114, v116, v117
	v_cvt_pk_bf16_f32 v115, v118, v119
	v_cvt_pk_bf16_f32 v116, v160, v161
	v_cvt_pk_bf16_f32 v117, v158, v159
	global_store_dwordx4 v[166:167], v[114:117], off offset:256
	s_and_saveexec_b64 s[22:23], s[2:3]
	s_cbranch_execz .LBB0_360
	s_waitcnt lgkmcnt(0)
	v_add_f32_e32 v112, v112, v113
	v_mul_f32_e32 v112, 0x4f800000, v112
	v_trunc_f32_e32 v112, v112
	v_mul_f32_e32 v113, 0x2f800000, v112
	v_floor_f32_e32 v113, v113
	v_fmac_f32_e32 v112, 0xcf800000, v113
	v_cvt_u32_f32_e32 v112, v112
	v_cvt_u32_f32_e32 v113, v113
	v_lshl_add_u64 v[114:115], v[146:147], 3, s[12:13]
	global_atomic_add_x2 v[114:115], v[112:113], off
; __device__ __forceinline__ float ss_scale(const u64* ss, int row) { return __builtin_amdgcn_rsqf((float)ss[row] * (1.f / 4294967296.f / 1024.f) + EPS); }
; __device__ __forceinline__ u64 ss_fix(float q) { return (u64)(q * 4294967296.f); }
;     __device__ __forceinline__ void operator()(const f32x4 (&acc)[2][2][4][2], const pg8::Unit& u, int wr, int wc, int fr, int fq) const {
;     ...
;         for (int ai = 0; ai < 2; ++ai)
; #pragma unroll
;             for (int m = 0; m < 4; ++m) {
;                 const int row = row0 + ai * 128 + m * 16;
;                 float q = 0.f, qw = 0.f, sh = 1.f;
;                 if constexpr (MODE == 2) sh = ss_scale(rss, row);
; #pragma unroll
;                 for (int bj = 0; bj < 2; ++bj) {
;                     const int c = col0 + bj * 128;
;                     const u32x4 rb = *(const u32x4*)(hb + (size_t)row * DM + c);
;                     f32x4 r0 = {bflo(rb.x), bfhi(rb.x), bflo(rb.y), bfhi(rb.y)}, r1 = {bflo(rb.z), bfhi(rb.z), bflo(rb.w), bfhi(rb.w)};
;                     if constexpr (MODE == 2) { r0 = r0 * sh * g0[bj]; r1 = r1 * sh * g1[bj]; }
;                     const f32x4 v0 = r0 + acc[ai][bj][m][0], v1 = r1 + acc[ai][bj][m][1];
;                     if constexpr (WF32) { *(f32x4*)(out + (size_t)row * DM + c) = v0; *(f32x4*)(out + (size_t)row * DM + c + 4) = v1; }
;                     u32x4 w; w.x = pkbf(v0[0], v0[1]); w.y = pkbf(v0[2], v0[3]); w.z = pkbf(v1[0], v1[1]); w.w = pkbf(v1[2], v1[3]);
;                     *(u32x4*)(hb + (size_t)row * DM + c) = w;
;                     const f32x4 s0 = v0 * v0, s1 = v1 * v1;
;                     q += (s0[0] + s0[1]) + (s0[2] + s0[3]) + (s1[0] + s1[1]) + (s1[2] + s1[3]);
;                     if constexpr (MODE == 1) { const f32x4 t0 = s0 * g0[bj], t1 = s1 * g1[bj]; qw += (t0[0] + t0[1]) + (t0[2] + t0[3]) + (t1[0] + t1[1]) + (t1[2] + t1[3]); }
;                 }
;                 q += __shfl_xor(q, 16); q += __shfl_xor(q, 32);
;                 if constexpr (MODE == 1) { qw += __shfl_xor(qw, 16); qw += __shfl_xor(qw, 32); }
;                 if (fq == 0) {
;                     __hip_atomic_fetch_add(ssn + row, ss_fix(q), __ATOMIC_RELAXED, __HIP_MEMORY_SCOPE_AGENT);
;                     if constexpr (MODE == 1) __hip_atomic_fetch_add(ssw + row, ss_fix(qw), __ATOMIC_RELAXED, __HIP_MEMORY_SCOPE_AGENT);
;                 }
;             }
.LBB0_360:
	s_or_b64 exec, exec, s[22:23]
	v_or_b32_e32 v112, 16, v146
	s_waitcnt lgkmcnt(0)
	v_ashrrev_i32_e32 v113, 31, v112
	v_lshlrev_b64 v[114:115], 11, v[112:113]
	v_lshl_add_u64 v[114:115], s[10:11], 0, v[114:115]
	v_lshl_add_u64 v[122:123], v[144:145], 1, v[114:115]
	s_nop 0
	s_nop 0
	s_waitcnt vmcnt(12)
	v_lshlrev_b32_e32 v124, 16, v184
	v_and_b32_e32 v125, 0xffff0000, v184
	v_lshlrev_b32_e32 v114, 16, v185
	v_and_b32_e32 v115, 0xffff0000, v185
	v_lshlrev_b32_e32 v126, 16, v186
	v_and_b32_e32 v127, 0xffff0000, v186
	v_lshlrev_b32_e32 v116, 16, v187
	v_and_b32_e32 v117, 0xffff0000, v187
	s_waitcnt vmcnt(11)
	v_lshlrev_b32_e32 v158, 16, v188
	v_and_b32_e32 v159, 0xffff0000, v188
	v_lshlrev_b32_e32 v118, 16, v189
	v_and_b32_e32 v119, 0xffff0000, v189
	v_lshlrev_b32_e32 v160, 16, v190
	v_and_b32_e32 v161, 0xffff0000, v190
	v_lshlrev_b32_e32 v120, 16, v191
	v_and_b32_e32 v121, 0xffff0000, v191
	s_mov_b32 s100, 0x50000
	s_mov_b32 s101, 0
	v_lshl_add_u64 v[222:223], v[220:221], 0, s[100:101]
	global_load_dwordx4 v[184:187], v[222:223], off
	global_load_dwordx4 v[188:191], v[222:223], off offset:256
	v_pk_add_f32 v[110:111], v[110:111], v[114:115]
	v_pk_add_f32 v[108:109], v[108:109], v[124:125]
	v_pk_add_f32 v[106:107], v[106:107], v[116:117]
	v_pk_add_f32 v[102:103], v[102:103], v[118:119]
	v_pk_add_f32 v[100:101], v[100:101], v[158:159]
	v_pk_add_f32 v[104:105], v[104:105], v[126:127]
	v_pk_add_f32 v[114:115], v[98:99], v[120:121]
	v_pk_add_f32 v[116:117], v[96:97], v[160:161]
	v_cvt_pk_bf16_f32 v96, v108, v109
	v_cvt_pk_bf16_f32 v97, v110, v111
	v_pk_mul_f32 v[98:99], v[110:111], v[110:111]
	v_pk_mul_f32 v[108:109], v[108:109], v[108:109]
	v_pk_mul_f32 v[110:111], v[106:107], v[106:107]
	v_pk_mul_f32 v[120:121], v[102:103], v[102:103]
	v_pk_mul_f32 v[124:125], v[100:101], v[100:101]
	v_pk_mul_f32 v[118:119], v[104:105], v[104:105]
	v_pk_mul_f32 v[158:159], v[116:117], v[116:117]
	v_add_f32_e32 v108, v108, v109
	v_add_f32_e32 v98, v98, v99
	v_add_f32_e32 v109, v110, v111
	v_add_f32_e32 v110, v124, v125
	v_add_f32_e32 v111, v120, v121
	v_pk_mul_f32 v[126:127], v[114:115], v[114:115]
	v_add_f32_e32 v99, v118, v119
	v_add_f32_e32 v118, v158, v159
	v_add_f32_e32 v98, v108, v98
	v_add_f32_e32 v108, v110, v111
	v_add_f32_e32 v119, v126, v127
	v_add_f32_e32 v98, v99, v98
	v_add_f32_e32 v99, v118, v108
	v_add_f32_e32 v98, v109, v98
	v_add_f32_e32 v99, v119, v99
	v_add_f32_e32 v108, v98, v99
	ds_bpermute_b32 v109, v157, v108
	v_cvt_pk_bf16_f32 v98, v104, v105
	v_cvt_pk_bf16_f32 v99, v106, v107
	global_store_dwordx4 v[122:123], v[96:99], off
	s_waitcnt lgkmcnt(0)
	s_nop 0
	v_add_f32_e32 v96, v108, v109
	ds_bpermute_b32 v97, v156, v96
	v_cvt_pk_bf16_f32 v98, v100, v101
	v_cvt_pk_bf16_f32 v99, v102, v103
	v_cvt_pk_bf16_f32 v100, v116, v117
	v_cvt_pk_bf16_f32 v101, v114, v115
	global_store_dwordx4 v[122:123], v[98:101], off offset:256
	s_and_saveexec_b64 s[22:23], s[2:3]
	s_cbranch_execz .LBB0_362
	s_waitcnt lgkmcnt(0)
	v_add_f32_e32 v96, v96, v97
	v_mul_f32_e32 v96, 0x4f800000, v96
	v_trunc_f32_e32 v96, v96
	v_mul_f32_e32 v97, 0x2f800000, v96
	v_floor_f32_e32 v97, v97
	v_fmac_f32_e32 v96, 0xcf800000, v97
	v_cvt_u32_f32_e32 v96, v96
	v_cvt_u32_f32_e32 v97, v97
	v_lshl_add_u64 v[98:99], v[112:113], 3, s[12:13]
	global_atomic_add_x2 v[98:99], v[96:97], off
.LBB0_362:
	s_or_b64 exec, exec, s[22:23]
	v_or_b32_e32 v96, 32, v146
	s_waitcnt lgkmcnt(0)
	v_ashrrev_i32_e32 v97, 31, v96
	v_lshlrev_b64 v[98:99], 11, v[96:97]
	v_lshl_add_u64 v[98:99], s[10:11], 0, v[98:99]
	v_lshl_add_u64 v[106:107], v[144:145], 1, v[98:99]
	s_nop 0
	s_nop 0
	s_waitcnt vmcnt(15)
	v_lshlrev_b32_e32 v108, 16, v192
	v_and_b32_e32 v109, 0xffff0000, v192
	v_lshlrev_b32_e32 v98, 16, v193
	v_and_b32_e32 v99, 0xffff0000, v193
	v_lshlrev_b32_e32 v110, 16, v194
	v_and_b32_e32 v111, 0xffff0000, v194
	v_lshlrev_b32_e32 v100, 16, v195
	v_and_b32_e32 v101, 0xffff0000, v195
	s_waitcnt vmcnt(14)
	v_lshlrev_b32_e32 v112, 16, v200
	v_and_b32_e32 v113, 0xffff0000, v200
	v_lshlrev_b32_e32 v102, 16, v201
	v_and_b32_e32 v103, 0xffff0000, v201
	v_lshlrev_b32_e32 v114, 16, v202
	v_and_b32_e32 v115, 0xffff0000, v202
	v_lshlrev_b32_e32 v104, 16, v203
	v_and_b32_e32 v105, 0xffff0000, v203
	s_mov_b32 s100, 0x58000
	s_mov_b32 s101, 0
	v_lshl_add_u64 v[222:223], v[220:221], 0, s[100:101]
	global_load_dwordx4 v[192:195], v[222:223], off
	global_load_dwordx4 v[200:203], v[222:223], off offset:256
	v_pk_add_f32 v[94:95], v[94:95], v[98:99]
	v_pk_add_f32 v[92:93], v[92:93], v[108:109]
	v_pk_add_f32 v[90:91], v[90:91], v[100:101]
	v_pk_add_f32 v[86:87], v[86:87], v[102:103]
	v_pk_add_f32 v[84:85], v[84:85], v[112:113]
	v_pk_add_f32 v[88:89], v[88:89], v[110:111]
	v_pk_add_f32 v[98:99], v[82:83], v[104:105]
	v_pk_add_f32 v[100:101], v[80:81], v[114:115]
	v_cvt_pk_bf16_f32 v80, v92, v93
	v_cvt_pk_bf16_f32 v81, v94, v95
	v_pk_mul_f32 v[82:83], v[94:95], v[94:95]
	v_pk_mul_f32 v[92:93], v[92:93], v[92:93]
	v_pk_mul_f32 v[94:95], v[90:91], v[90:91]
	v_pk_mul_f32 v[104:105], v[86:87], v[86:87]
	v_pk_mul_f32 v[108:109], v[84:85], v[84:85]
	v_pk_mul_f32 v[102:103], v[88:89], v[88:89]
	v_pk_mul_f32 v[112:113], v[100:101], v[100:101]
	v_add_f32_e32 v92, v92, v93
	v_add_f32_e32 v82, v82, v83
	v_add_f32_e32 v93, v94, v95
	v_add_f32_e32 v94, v108, v109
	v_add_f32_e32 v95, v104, v105
	v_pk_mul_f32 v[110:111], v[98:99], v[98:99]
	v_add_f32_e32 v83, v102, v103
	v_add_f32_e32 v102, v112, v113
	v_add_f32_e32 v82, v92, v82
	v_add_f32_e32 v92, v94, v95
	v_add_f32_e32 v103, v110, v111
	v_add_f32_e32 v82, v83, v82
	v_add_f32_e32 v83, v102, v92
	v_add_f32_e32 v82, v93, v82
	v_add_f32_e32 v83, v103, v83
	v_add_f32_e32 v92, v82, v83
	ds_bpermute_b32 v93, v157, v92
	v_cvt_pk_bf16_f32 v82, v88, v89
	v_cvt_pk_bf16_f32 v83, v90, v91
	global_store_dwordx4 v[106:107], v[80:83], off
	s_waitcnt lgkmcnt(0)
	s_nop 0
	v_add_f32_e32 v80, v92, v93
	ds_bpermute_b32 v81, v156, v80
	v_cvt_pk_bf16_f32 v82, v84, v85
	v_cvt_pk_bf16_f32 v83, v86, v87
	v_cvt_pk_bf16_f32 v84, v100, v101
	v_cvt_pk_bf16_f32 v85, v98, v99
	global_store_dwordx4 v[106:107], v[82:85], off offset:256
	s_and_saveexec_b64 s[22:23], s[2:3]
	s_cbranch_execz .LBB0_364
	s_waitcnt lgkmcnt(0)
	v_add_f32_e32 v80, v80, v81
	v_mul_f32_e32 v80, 0x4f800000, v80
	v_trunc_f32_e32 v80, v80
	v_mul_f32_e32 v81, 0x2f800000, v80
	v_floor_f32_e32 v81, v81
	v_fmac_f32_e32 v80, 0xcf800000, v81
	v_cvt_u32_f32_e32 v80, v80
	v_cvt_u32_f32_e32 v81, v81
	v_lshl_add_u64 v[82:83], v[96:97], 3, s[12:13]
	global_atomic_add_x2 v[82:83], v[80:81], off
; __device__ __forceinline__ float ss_scale(const u64* ss, int row) { return __builtin_amdgcn_rsqf((float)ss[row] * (1.f / 4294967296.f / 1024.f) + EPS); }
; __device__ __forceinline__ u64 ss_fix(float q) { return (u64)(q * 4294967296.f); }
;     __device__ __forceinline__ void operator()(const f32x4 (&acc)[2][2][4][2], const pg8::Unit& u, int wr, int wc, int fr, int fq) const {
;     ...
;         for (int ai = 0; ai < 2; ++ai)
; #pragma unroll
;             for (int m = 0; m < 4; ++m) {
;                 const int row = row0 + ai * 128 + m * 16;
;                 float q = 0.f, qw = 0.f, sh = 1.f;
;                 if constexpr (MODE == 2) sh = ss_scale(rss, row);
; #pragma unroll
;                 for (int bj = 0; bj < 2; ++bj) {
;                     const int c = col0 + bj * 128;
;                     const u32x4 rb = *(const u32x4*)(hb + (size_t)row * DM + c);
;                     f32x4 r0 = {bflo(rb.x), bfhi(rb.x), bflo(rb.y), bfhi(rb.y)}, r1 = {bflo(rb.z), bfhi(rb.z), bflo(rb.w), bfhi(rb.w)};
;                     if constexpr (MODE == 2) { r0 = r0 * sh * g0[bj]; r1 = r1 * sh * g1[bj]; }
;                     const f32x4 v0 = r0 + acc[ai][bj][m][0], v1 = r1 + acc[ai][bj][m][1];
;                     if constexpr (WF32) { *(f32x4*)(out + (size_t)row * DM + c) = v0; *(f32x4*)(out + (size_t)row * DM + c + 4) = v1; }
;                     u32x4 w; w.x = pkbf(v0[0], v0[1]); w.y = pkbf(v0[2], v0[3]); w.z = pkbf(v1[0], v1[1]); w.w = pkbf(v1[2], v1[3]);
;                     *(u32x4*)(hb + (size_t)row * DM + c) = w;
;                     const f32x4 s0 = v0 * v0, s1 = v1 * v1;
;                     q += (s0[0] + s0[1]) + (s0[2] + s0[3]) + (s1[0] + s1[1]) + (s1[2] + s1[3]);
;                     if constexpr (MODE == 1) { const f32x4 t0 = s0 * g0[bj], t1 = s1 * g1[bj]; qw += (t0[0] + t0[1]) + (t0[2] + t0[3]) + (t1[0] + t1[1]) + (t1[2] + t1[3]); }
;                 }
;                 q += __shfl_xor(q, 16); q += __shfl_xor(q, 32);
;                 if constexpr (MODE == 1) { qw += __shfl_xor(qw, 16); qw += __shfl_xor(qw, 32); }
;                 if (fq == 0) {
;                     __hip_atomic_fetch_add(ssn + row, ss_fix(q), __ATOMIC_RELAXED, __HIP_MEMORY_SCOPE_AGENT);
;                     if constexpr (MODE == 1) __hip_atomic_fetch_add(ssw + row, ss_fix(qw), __ATOMIC_RELAXED, __HIP_MEMORY_SCOPE_AGENT);
;                 }
;             }
.LBB0_364:
	s_or_b64 exec, exec, s[22:23]
	v_or_b32_e32 v80, 48, v146
	s_waitcnt lgkmcnt(0)
	v_ashrrev_i32_e32 v81, 31, v80
	v_lshlrev_b64 v[82:83], 11, v[80:81]
	v_lshl_add_u64 v[82:83], s[10:11], 0, v[82:83]
	v_lshl_add_u64 v[90:91], v[144:145], 1, v[82:83]
	s_nop 0
	s_nop 0
	s_waitcnt vmcnt(18)
	v_lshlrev_b32_e32 v92, 16, v204
	v_and_b32_e32 v93, 0xffff0000, v204
	v_lshlrev_b32_e32 v82, 16, v205
	v_and_b32_e32 v83, 0xffff0000, v205
	v_lshlrev_b32_e32 v94, 16, v206
	v_and_b32_e32 v95, 0xffff0000, v206
	v_lshlrev_b32_e32 v84, 16, v207
	v_and_b32_e32 v85, 0xffff0000, v207
	s_waitcnt vmcnt(17)
	v_lshlrev_b32_e32 v96, 16, v208
	v_and_b32_e32 v97, 0xffff0000, v208
	v_lshlrev_b32_e32 v86, 16, v209
	v_and_b32_e32 v87, 0xffff0000, v209
	v_lshlrev_b32_e32 v98, 16, v210
	v_and_b32_e32 v99, 0xffff0000, v210
	v_lshlrev_b32_e32 v88, 16, v211
	v_and_b32_e32 v89, 0xffff0000, v211
	v_pk_add_f32 v[78:79], v[78:79], v[82:83]
	v_pk_add_f32 v[76:77], v[76:77], v[92:93]
	v_pk_add_f32 v[74:75], v[74:75], v[84:85]
	v_pk_add_f32 v[70:71], v[70:71], v[86:87]
	v_pk_add_f32 v[68:69], v[68:69], v[96:97]
	v_pk_add_f32 v[72:73], v[72:73], v[94:95]
	v_pk_add_f32 v[82:83], v[66:67], v[88:89]
	v_pk_add_f32 v[84:85], v[64:65], v[98:99]
	v_cvt_pk_bf16_f32 v64, v76, v77
	v_cvt_pk_bf16_f32 v65, v78, v79
	v_pk_mul_f32 v[66:67], v[78:79], v[78:79]
	v_pk_mul_f32 v[76:77], v[76:77], v[76:77]
	v_pk_mul_f32 v[78:79], v[74:75], v[74:75]
	v_pk_mul_f32 v[88:89], v[70:71], v[70:71]
	v_pk_mul_f32 v[92:93], v[68:69], v[68:69]
	v_pk_mul_f32 v[86:87], v[72:73], v[72:73]
	v_pk_mul_f32 v[96:97], v[84:85], v[84:85]
	v_add_f32_e32 v76, v76, v77
	v_add_f32_e32 v66, v66, v67
	v_add_f32_e32 v77, v78, v79
	v_add_f32_e32 v78, v92, v93
	v_add_f32_e32 v79, v88, v89
	v_pk_mul_f32 v[94:95], v[82:83], v[82:83]
	v_add_f32_e32 v67, v86, v87
	v_add_f32_e32 v86, v96, v97
	v_add_f32_e32 v66, v76, v66
	v_add_f32_e32 v76, v78, v79
	v_add_f32_e32 v87, v94, v95
	v_add_f32_e32 v66, v67, v66
	v_add_f32_e32 v67, v86, v76
	v_add_f32_e32 v66, v77, v66
	v_add_f32_e32 v67, v87, v67
	v_add_f32_e32 v76, v66, v67
	ds_bpermute_b32 v77, v157, v76
	v_cvt_pk_bf16_f32 v66, v72, v73
	v_cvt_pk_bf16_f32 v67, v74, v75
	global_store_dwordx4 v[90:91], v[64:67], off
	s_waitcnt lgkmcnt(0)
	s_nop 0
	v_add_f32_e32 v64, v76, v77
	ds_bpermute_b32 v65, v156, v64
	v_cvt_pk_bf16_f32 v66, v68, v69
	v_cvt_pk_bf16_f32 v67, v70, v71
	v_cvt_pk_bf16_f32 v68, v84, v85
	v_cvt_pk_bf16_f32 v69, v82, v83
	global_store_dwordx4 v[90:91], v[66:69], off offset:256
	s_and_saveexec_b64 s[22:23], s[2:3]
	s_cbranch_execz .LBB0_366
	s_waitcnt lgkmcnt(0)
	v_add_f32_e32 v64, v64, v65
	v_mul_f32_e32 v64, 0x4f800000, v64
	v_trunc_f32_e32 v64, v64
	v_mul_f32_e32 v65, 0x2f800000, v64
	v_floor_f32_e32 v65, v65
	v_fmac_f32_e32 v64, 0xcf800000, v65
	v_cvt_u32_f32_e32 v64, v64
	v_cvt_u32_f32_e32 v65, v65
	v_lshl_add_u64 v[66:67], v[80:81], 3, s[12:13]
	global_atomic_add_x2 v[66:67], v[64:65], off
.LBB0_366:
	s_or_b64 exec, exec, s[22:23]
	v_add_u32_e32 v64, 0x80, v146
	s_waitcnt lgkmcnt(0)
	v_ashrrev_i32_e32 v65, 31, v64
	v_lshlrev_b64 v[66:67], 11, v[64:65]
	v_lshl_add_u64 v[66:67], s[10:11], 0, v[66:67]
	v_lshl_add_u64 v[74:75], v[144:145], 1, v[66:67]
	s_nop 0
	s_nop 0
	s_waitcnt vmcnt(19)
	v_lshlrev_b32_e32 v76, 16, v212
	v_and_b32_e32 v77, 0xffff0000, v212
	v_lshlrev_b32_e32 v66, 16, v213
	v_and_b32_e32 v67, 0xffff0000, v213
	v_lshlrev_b32_e32 v78, 16, v214
	v_and_b32_e32 v79, 0xffff0000, v214
	v_lshlrev_b32_e32 v68, 16, v215
	v_and_b32_e32 v69, 0xffff0000, v215
	s_waitcnt vmcnt(18)
	v_lshlrev_b32_e32 v80, 16, v216
	v_and_b32_e32 v81, 0xffff0000, v216
	v_lshlrev_b32_e32 v70, 16, v217
	v_and_b32_e32 v71, 0xffff0000, v217
	v_lshlrev_b32_e32 v82, 16, v218
	v_and_b32_e32 v83, 0xffff0000, v218
	v_lshlrev_b32_e32 v72, 16, v219
	v_and_b32_e32 v73, 0xffff0000, v219
	v_pk_add_f32 v[62:63], v[62:63], v[66:67]
	v_pk_add_f32 v[60:61], v[60:61], v[76:77]
	v_pk_add_f32 v[58:59], v[58:59], v[68:69]
	v_pk_add_f32 v[54:55], v[54:55], v[70:71]
	v_pk_add_f32 v[52:53], v[52:53], v[80:81]
	v_pk_add_f32 v[56:57], v[56:57], v[78:79]
	v_pk_add_f32 v[66:67], v[50:51], v[72:73]
	v_pk_add_f32 v[68:69], v[48:49], v[82:83]
	v_cvt_pk_bf16_f32 v48, v60, v61
	v_cvt_pk_bf16_f32 v49, v62, v63
	v_pk_mul_f32 v[50:51], v[62:63], v[62:63]
	v_pk_mul_f32 v[60:61], v[60:61], v[60:61]
	v_pk_mul_f32 v[62:63], v[58:59], v[58:59]
	v_pk_mul_f32 v[72:73], v[54:55], v[54:55]
	v_pk_mul_f32 v[76:77], v[52:53], v[52:53]
	v_pk_mul_f32 v[70:71], v[56:57], v[56:57]
	v_pk_mul_f32 v[80:81], v[68:69], v[68:69]
	v_add_f32_e32 v60, v60, v61
	v_add_f32_e32 v50, v50, v51
	v_add_f32_e32 v61, v62, v63
	v_add_f32_e32 v62, v76, v77
	v_add_f32_e32 v63, v72, v73
	v_pk_mul_f32 v[78:79], v[66:67], v[66:67]
	v_add_f32_e32 v51, v70, v71
	v_add_f32_e32 v70, v80, v81
	v_add_f32_e32 v50, v60, v50
	v_add_f32_e32 v60, v62, v63
	v_add_f32_e32 v71, v78, v79
	v_add_f32_e32 v50, v51, v50
	v_add_f32_e32 v51, v70, v60
	v_add_f32_e32 v50, v61, v50
	v_add_f32_e32 v51, v71, v51
	v_add_f32_e32 v60, v50, v51
	ds_bpermute_b32 v61, v157, v60
	v_cvt_pk_bf16_f32 v50, v56, v57
	v_cvt_pk_bf16_f32 v51, v58, v59
	global_store_dwordx4 v[74:75], v[48:51], off
	s_waitcnt lgkmcnt(0)
	s_nop 0
	v_add_f32_e32 v48, v60, v61
	ds_bpermute_b32 v49, v156, v48
	v_cvt_pk_bf16_f32 v50, v52, v53
	v_cvt_pk_bf16_f32 v51, v54, v55
	v_cvt_pk_bf16_f32 v52, v68, v69
	v_cvt_pk_bf16_f32 v53, v66, v67
	global_store_dwordx4 v[74:75], v[50:53], off offset:256
	s_and_saveexec_b64 s[22:23], s[2:3]
	s_cbranch_execz .LBB0_368
	s_waitcnt lgkmcnt(0)
	v_add_f32_e32 v48, v48, v49
	v_mul_f32_e32 v48, 0x4f800000, v48
	v_trunc_f32_e32 v48, v48
	v_mul_f32_e32 v49, 0x2f800000, v48
	v_floor_f32_e32 v49, v49
	v_fmac_f32_e32 v48, 0xcf800000, v49
	v_cvt_u32_f32_e32 v48, v48
	v_cvt_u32_f32_e32 v49, v49
	v_lshl_add_u64 v[50:51], v[64:65], 3, s[12:13]
	global_atomic_add_x2 v[50:51], v[48:49], off
; __device__ __forceinline__ float ss_scale(const u64* ss, int row) { return __builtin_amdgcn_rsqf((float)ss[row] * (1.f / 4294967296.f / 1024.f) + EPS); }
; __device__ __forceinline__ u64 ss_fix(float q) { return (u64)(q * 4294967296.f); }
;     __device__ __forceinline__ void operator()(const f32x4 (&acc)[2][2][4][2], const pg8::Unit& u, int wr, int wc, int fr, int fq) const {
;     ...
;         for (int ai = 0; ai < 2; ++ai)
; #pragma unroll
;             for (int m = 0; m < 4; ++m) {
;                 const int row = row0 + ai * 128 + m * 16;
;                 float q = 0.f, qw = 0.f, sh = 1.f;
;                 if constexpr (MODE == 2) sh = ss_scale(rss, row);
; #pragma unroll
;                 for (int bj = 0; bj < 2; ++bj) {
;                     const int c = col0 + bj * 128;
;                     const u32x4 rb = *(const u32x4*)(hb + (size_t)row * DM + c);
;                     f32x4 r0 = {bflo(rb.x), bfhi(rb.x), bflo(rb.y), bfhi(rb.y)}, r1 = {bflo(rb.z), bfhi(rb.z), bflo(rb.w), bfhi(rb.w)};
;                     if constexpr (MODE == 2) { r0 = r0 * sh * g0[bj]; r1 = r1 * sh * g1[bj]; }
;                     const f32x4 v0 = r0 + acc[ai][bj][m][0], v1 = r1 + acc[ai][bj][m][1];
;                     if constexpr (WF32) { *(f32x4*)(out + (size_t)row * DM + c) = v0; *(f32x4*)(out + (size_t)row * DM + c + 4) = v1; }
;                     u32x4 w; w.x = pkbf(v0[0], v0[1]); w.y = pkbf(v0[2], v0[3]); w.z = pkbf(v1[0], v1[1]); w.w = pkbf(v1[2], v1[3]);
;                     *(u32x4*)(hb + (size_t)row * DM + c) = w;
;                     const f32x4 s0 = v0 * v0, s1 = v1 * v1;
;                     q += (s0[0] + s0[1]) + (s0[2] + s0[3]) + (s1[0] + s1[1]) + (s1[2] + s1[3]);
;                     if constexpr (MODE == 1) { const f32x4 t0 = s0 * g0[bj], t1 = s1 * g1[bj]; qw += (t0[0] + t0[1]) + (t0[2] + t0[3]) + (t1[0] + t1[1]) + (t1[2] + t1[3]); }
;                 }
;                 q += __shfl_xor(q, 16); q += __shfl_xor(q, 32);
;                 if constexpr (MODE == 1) { qw += __shfl_xor(qw, 16); qw += __shfl_xor(qw, 32); }
;                 if (fq == 0) {
;                     __hip_atomic_fetch_add(ssn + row, ss_fix(q), __ATOMIC_RELAXED, __HIP_MEMORY_SCOPE_AGENT);
;                     if constexpr (MODE == 1) __hip_atomic_fetch_add(ssw + row, ss_fix(qw), __ATOMIC_RELAXED, __HIP_MEMORY_SCOPE_AGENT);
;                 }
;             }
.LBB0_368:
	s_or_b64 exec, exec, s[22:23]
	v_add_u32_e32 v48, 0x90, v146
	s_waitcnt lgkmcnt(0)
	v_ashrrev_i32_e32 v49, 31, v48
	v_lshlrev_b64 v[50:51], 11, v[48:49]
	v_lshl_add_u64 v[50:51], s[10:11], 0, v[50:51]
	v_lshl_add_u64 v[58:59], v[144:145], 1, v[50:51]
	s_nop 0
	s_nop 0
	s_waitcnt vmcnt(20)
	v_lshlrev_b32_e32 v60, 16, v176
	v_and_b32_e32 v61, 0xffff0000, v176
	v_lshlrev_b32_e32 v50, 16, v177
	v_and_b32_e32 v51, 0xffff0000, v177
	v_lshlrev_b32_e32 v62, 16, v178
	v_and_b32_e32 v63, 0xffff0000, v178
	v_lshlrev_b32_e32 v52, 16, v179
	v_and_b32_e32 v53, 0xffff0000, v179
	s_waitcnt vmcnt(19)
	v_lshlrev_b32_e32 v64, 16, v180
	v_and_b32_e32 v65, 0xffff0000, v180
	v_lshlrev_b32_e32 v54, 16, v181
	v_and_b32_e32 v55, 0xffff0000, v181
	v_lshlrev_b32_e32 v66, 16, v182
	v_and_b32_e32 v67, 0xffff0000, v182
	v_lshlrev_b32_e32 v56, 16, v183
	v_and_b32_e32 v57, 0xffff0000, v183
	v_pk_add_f32 v[46:47], v[46:47], v[50:51]
	v_pk_add_f32 v[44:45], v[44:45], v[60:61]
	v_pk_add_f32 v[42:43], v[42:43], v[52:53]
	v_pk_add_f32 v[38:39], v[38:39], v[54:55]
	v_pk_add_f32 v[36:37], v[36:37], v[64:65]
	v_pk_add_f32 v[40:41], v[40:41], v[62:63]
	v_pk_add_f32 v[50:51], v[34:35], v[56:57]
	v_pk_add_f32 v[52:53], v[32:33], v[66:67]
	v_cvt_pk_bf16_f32 v32, v44, v45
	v_cvt_pk_bf16_f32 v33, v46, v47
	v_pk_mul_f32 v[34:35], v[46:47], v[46:47]
	v_pk_mul_f32 v[44:45], v[44:45], v[44:45]
	v_pk_mul_f32 v[46:47], v[42:43], v[42:43]
	v_pk_mul_f32 v[56:57], v[38:39], v[38:39]
	v_pk_mul_f32 v[60:61], v[36:37], v[36:37]
	v_pk_mul_f32 v[54:55], v[40:41], v[40:41]
	v_pk_mul_f32 v[64:65], v[52:53], v[52:53]
	v_add_f32_e32 v44, v44, v45
	v_add_f32_e32 v34, v34, v35
	v_add_f32_e32 v45, v46, v47
	v_add_f32_e32 v46, v60, v61
	v_add_f32_e32 v47, v56, v57
	v_pk_mul_f32 v[62:63], v[50:51], v[50:51]
	v_add_f32_e32 v35, v54, v55
	v_add_f32_e32 v54, v64, v65
	v_add_f32_e32 v34, v44, v34
	v_add_f32_e32 v44, v46, v47
	v_add_f32_e32 v55, v62, v63
	v_add_f32_e32 v34, v35, v34
	v_add_f32_e32 v35, v54, v44
	v_add_f32_e32 v34, v45, v34
	v_add_f32_e32 v35, v55, v35
	v_add_f32_e32 v44, v34, v35
	ds_bpermute_b32 v45, v157, v44
	v_cvt_pk_bf16_f32 v34, v40, v41
	v_cvt_pk_bf16_f32 v35, v42, v43
	global_store_dwordx4 v[58:59], v[32:35], off
	s_waitcnt lgkmcnt(0)
	s_nop 0
	v_add_f32_e32 v32, v44, v45
	ds_bpermute_b32 v33, v156, v32
	v_cvt_pk_bf16_f32 v34, v36, v37
	v_cvt_pk_bf16_f32 v35, v38, v39
	v_cvt_pk_bf16_f32 v36, v52, v53
	v_cvt_pk_bf16_f32 v37, v50, v51
	global_store_dwordx4 v[58:59], v[34:37], off offset:256
	s_and_saveexec_b64 s[22:23], s[2:3]
	s_cbranch_execz .LBB0_370
	s_waitcnt lgkmcnt(0)
	v_add_f32_e32 v32, v32, v33
	v_mul_f32_e32 v32, 0x4f800000, v32
	v_trunc_f32_e32 v32, v32
	v_mul_f32_e32 v33, 0x2f800000, v32
	v_floor_f32_e32 v33, v33
	v_fmac_f32_e32 v32, 0xcf800000, v33
	v_cvt_u32_f32_e32 v32, v32
	v_cvt_u32_f32_e32 v33, v33
	v_lshl_add_u64 v[34:35], v[48:49], 3, s[12:13]
	global_atomic_add_x2 v[34:35], v[32:33], off
; __device__ __forceinline__ float ss_scale(const u64* ss, int row) { return __builtin_amdgcn_rsqf((float)ss[row] * (1.f / 4294967296.f / 1024.f) + EPS); }
; __device__ __forceinline__ u64 ss_fix(float q) { return (u64)(q * 4294967296.f); }
;     __device__ __forceinline__ void operator()(const f32x4 (&acc)[2][2][4][2], const pg8::Unit& u, int wr, int wc, int fr, int fq) const {
;     ...
;         for (int ai = 0; ai < 2; ++ai)
; #pragma unroll
;             for (int m = 0; m < 4; ++m) {
;                 const int row = row0 + ai * 128 + m * 16;
;                 float q = 0.f, qw = 0.f, sh = 1.f;
;                 if constexpr (MODE == 2) sh = ss_scale(rss, row);
; #pragma unroll
;                 for (int bj = 0; bj < 2; ++bj) {
;                     const int c = col0 + bj * 128;
;                     const u32x4 rb = *(const u32x4*)(hb + (size_t)row * DM + c);
;                     f32x4 r0 = {bflo(rb.x), bfhi(rb.x), bflo(rb.y), bfhi(rb.y)}, r1 = {bflo(rb.z), bfhi(rb.z), bflo(rb.w), bfhi(rb.w)};
;                     if constexpr (MODE == 2) { r0 = r0 * sh * g0[bj]; r1 = r1 * sh * g1[bj]; }
;                     const f32x4 v0 = r0 + acc[ai][bj][m][0], v1 = r1 + acc[ai][bj][m][1];
;                     if constexpr (WF32) { *(f32x4*)(out + (size_t)row * DM + c) = v0; *(f32x4*)(out + (size_t)row * DM + c + 4) = v1; }
;                     u32x4 w; w.x = pkbf(v0[0], v0[1]); w.y = pkbf(v0[2], v0[3]); w.z = pkbf(v1[0], v1[1]); w.w = pkbf(v1[2], v1[3]);
;                     *(u32x4*)(hb + (size_t)row * DM + c) = w;
;                     const f32x4 s0 = v0 * v0, s1 = v1 * v1;
;                     q += (s0[0] + s0[1]) + (s0[2] + s0[3]) + (s1[0] + s1[1]) + (s1[2] + s1[3]);
;                     if constexpr (MODE == 1) { const f32x4 t0 = s0 * g0[bj], t1 = s1 * g1[bj]; qw += (t0[0] + t0[1]) + (t0[2] + t0[3]) + (t1[0] + t1[1]) + (t1[2] + t1[3]); }
;                 }
;                 q += __shfl_xor(q, 16); q += __shfl_xor(q, 32);
;                 if constexpr (MODE == 1) { qw += __shfl_xor(qw, 16); qw += __shfl_xor(qw, 32); }
;                 if (fq == 0) {
;                     __hip_atomic_fetch_add(ssn + row, ss_fix(q), __ATOMIC_RELAXED, __HIP_MEMORY_SCOPE_AGENT);
;                     if constexpr (MODE == 1) __hip_atomic_fetch_add(ssw + row, ss_fix(qw), __ATOMIC_RELAXED, __HIP_MEMORY_SCOPE_AGENT);
;                 }
;             }
.LBB0_370:
	s_or_b64 exec, exec, s[22:23]
	v_add_u32_e32 v32, 0xa0, v146
	s_waitcnt lgkmcnt(0)
	v_ashrrev_i32_e32 v33, 31, v32
	v_lshlrev_b64 v[34:35], 11, v[32:33]
	v_lshl_add_u64 v[34:35], s[10:11], 0, v[34:35]
	v_lshl_add_u64 v[42:43], v[144:145], 1, v[34:35]
	s_nop 0
	s_nop 0
	s_waitcnt vmcnt(18)
	v_lshlrev_b32_e32 v44, 16, v184
	v_and_b32_e32 v45, 0xffff0000, v184
	v_lshlrev_b32_e32 v34, 16, v185
	v_and_b32_e32 v35, 0xffff0000, v185
	v_lshlrev_b32_e32 v46, 16, v186
	v_and_b32_e32 v47, 0xffff0000, v186
	v_lshlrev_b32_e32 v36, 16, v187
	v_and_b32_e32 v37, 0xffff0000, v187
	s_waitcnt vmcnt(17)
	v_lshlrev_b32_e32 v48, 16, v188
	v_and_b32_e32 v49, 0xffff0000, v188
	v_lshlrev_b32_e32 v38, 16, v189
	v_and_b32_e32 v39, 0xffff0000, v189
	v_lshlrev_b32_e32 v50, 16, v190
	v_and_b32_e32 v51, 0xffff0000, v190
	v_lshlrev_b32_e32 v40, 16, v191
	v_and_b32_e32 v41, 0xffff0000, v191
	v_pk_add_f32 v[30:31], v[30:31], v[34:35]
	v_pk_add_f32 v[28:29], v[28:29], v[44:45]
	v_pk_add_f32 v[26:27], v[26:27], v[36:37]
	v_pk_add_f32 v[22:23], v[22:23], v[38:39]
	v_pk_add_f32 v[20:21], v[20:21], v[48:49]
	v_pk_add_f32 v[24:25], v[24:25], v[46:47]
	v_pk_add_f32 v[34:35], v[18:19], v[40:41]
	v_pk_add_f32 v[36:37], v[16:17], v[50:51]
	v_cvt_pk_bf16_f32 v16, v28, v29
	v_cvt_pk_bf16_f32 v17, v30, v31
	v_pk_mul_f32 v[18:19], v[30:31], v[30:31]
	v_pk_mul_f32 v[28:29], v[28:29], v[28:29]
	v_pk_mul_f32 v[30:31], v[26:27], v[26:27]
	v_pk_mul_f32 v[40:41], v[22:23], v[22:23]
	v_pk_mul_f32 v[44:45], v[20:21], v[20:21]
	v_pk_mul_f32 v[38:39], v[24:25], v[24:25]
	v_pk_mul_f32 v[48:49], v[36:37], v[36:37]
	v_add_f32_e32 v28, v28, v29
	v_add_f32_e32 v18, v18, v19
	v_add_f32_e32 v29, v30, v31
	v_add_f32_e32 v30, v44, v45
	v_add_f32_e32 v31, v40, v41
	v_pk_mul_f32 v[46:47], v[34:35], v[34:35]
	v_add_f32_e32 v19, v38, v39
	v_add_f32_e32 v38, v48, v49
	v_add_f32_e32 v18, v28, v18
	v_add_f32_e32 v28, v30, v31
	v_add_f32_e32 v39, v46, v47
	v_add_f32_e32 v18, v19, v18
	v_add_f32_e32 v19, v38, v28
	v_add_f32_e32 v18, v29, v18
	v_add_f32_e32 v19, v39, v19
	v_add_f32_e32 v28, v18, v19
	ds_bpermute_b32 v29, v157, v28
	v_cvt_pk_bf16_f32 v18, v24, v25
	v_cvt_pk_bf16_f32 v19, v26, v27
	global_store_dwordx4 v[42:43], v[16:19], off
	s_waitcnt lgkmcnt(0)
	s_nop 0
	v_add_f32_e32 v16, v28, v29
	ds_bpermute_b32 v17, v156, v16
	v_cvt_pk_bf16_f32 v18, v20, v21
	v_cvt_pk_bf16_f32 v19, v22, v23
	v_cvt_pk_bf16_f32 v20, v36, v37
	v_cvt_pk_bf16_f32 v21, v34, v35
	global_store_dwordx4 v[42:43], v[18:21], off offset:256
	s_and_saveexec_b64 s[22:23], s[2:3]
	s_cbranch_execz .LBB0_372
	s_waitcnt lgkmcnt(0)
	v_add_f32_e32 v16, v16, v17
	v_mul_f32_e32 v16, 0x4f800000, v16
	v_trunc_f32_e32 v16, v16
	v_mul_f32_e32 v17, 0x2f800000, v16
	v_floor_f32_e32 v17, v17
	v_fmac_f32_e32 v16, 0xcf800000, v17
	v_cvt_u32_f32_e32 v16, v16
	v_cvt_u32_f32_e32 v17, v17
	v_lshl_add_u64 v[18:19], v[32:33], 3, s[12:13]
	global_atomic_add_x2 v[18:19], v[16:17], off
.LBB0_372:
	s_or_b64 exec, exec, s[22:23]
	v_add_u32_e32 v16, 0xb0, v146
	s_waitcnt lgkmcnt(0)
	v_ashrrev_i32_e32 v17, 31, v16
	v_lshlrev_b64 v[18:19], 11, v[16:17]
	v_lshl_add_u64 v[18:19], s[10:11], 0, v[18:19]
	v_lshl_add_u64 v[26:27], v[144:145], 1, v[18:19]
	s_nop 0
	s_nop 0
	s_waitcnt vmcnt(16)
	v_lshlrev_b32_e32 v28, 16, v192
	v_and_b32_e32 v29, 0xffff0000, v192
	v_lshlrev_b32_e32 v18, 16, v193
	v_and_b32_e32 v19, 0xffff0000, v193
	v_lshlrev_b32_e32 v30, 16, v194
	v_and_b32_e32 v31, 0xffff0000, v194
	v_lshlrev_b32_e32 v20, 16, v195
	v_and_b32_e32 v21, 0xffff0000, v195
	s_waitcnt vmcnt(15)
	v_lshlrev_b32_e32 v32, 16, v200
	v_and_b32_e32 v33, 0xffff0000, v200
	v_lshlrev_b32_e32 v22, 16, v201
	v_and_b32_e32 v23, 0xffff0000, v201
	v_lshlrev_b32_e32 v34, 16, v202
	v_and_b32_e32 v35, 0xffff0000, v202
	v_lshlrev_b32_e32 v24, 16, v203
	v_and_b32_e32 v25, 0xffff0000, v203
	v_pk_add_f32 v[14:15], v[14:15], v[18:19]
	v_pk_add_f32 v[12:13], v[12:13], v[28:29]
	v_pk_add_f32 v[10:11], v[10:11], v[20:21]
	v_pk_add_f32 v[6:7], v[6:7], v[22:23]
	v_pk_add_f32 v[4:5], v[4:5], v[32:33]
	v_pk_add_f32 v[8:9], v[8:9], v[30:31]
	v_pk_add_f32 v[18:19], v[2:3], v[24:25]
	v_pk_add_f32 v[20:21], v[0:1], v[34:35]
	v_cvt_pk_bf16_f32 v0, v12, v13
	v_cvt_pk_bf16_f32 v1, v14, v15
	v_pk_mul_f32 v[2:3], v[14:15], v[14:15]
	v_pk_mul_f32 v[12:13], v[12:13], v[12:13]
	v_pk_mul_f32 v[14:15], v[10:11], v[10:11]
	v_pk_mul_f32 v[24:25], v[6:7], v[6:7]
	v_pk_mul_f32 v[28:29], v[4:5], v[4:5]
	v_pk_mul_f32 v[22:23], v[8:9], v[8:9]
	v_pk_mul_f32 v[32:33], v[20:21], v[20:21]
	v_add_f32_e32 v12, v12, v13
	v_add_f32_e32 v2, v2, v3
	v_add_f32_e32 v13, v14, v15
	v_add_f32_e32 v14, v28, v29
	v_add_f32_e32 v15, v24, v25
	v_pk_mul_f32 v[30:31], v[18:19], v[18:19]
	v_add_f32_e32 v3, v22, v23
	v_add_f32_e32 v22, v32, v33
	v_add_f32_e32 v2, v12, v2
	v_add_f32_e32 v12, v14, v15
	v_add_f32_e32 v23, v30, v31
	v_add_f32_e32 v2, v3, v2
	v_add_f32_e32 v3, v22, v12
	v_add_f32_e32 v2, v13, v2
	v_add_f32_e32 v3, v23, v3
	v_add_f32_e32 v12, v2, v3
	ds_bpermute_b32 v13, v157, v12
	v_cvt_pk_bf16_f32 v2, v8, v9
	v_cvt_pk_bf16_f32 v3, v10, v11
	global_store_dwordx4 v[26:27], v[0:3], off
	s_waitcnt lgkmcnt(0)
	s_nop 0
	v_add_f32_e32 v0, v12, v13
	ds_bpermute_b32 v1, v156, v0
	v_cvt_pk_bf16_f32 v2, v4, v5
	v_cvt_pk_bf16_f32 v3, v6, v7
	v_cvt_pk_bf16_f32 v4, v20, v21
	v_cvt_pk_bf16_f32 v5, v18, v19
	global_store_dwordx4 v[26:27], v[2:5], off offset:256
	s_and_saveexec_b64 s[22:23], s[2:3]
	s_cbranch_execz .LBB0_374
	s_waitcnt lgkmcnt(0)
	v_add_f32_e32 v0, v0, v1
	v_mul_f32_e32 v0, 0x4f800000, v0
	v_trunc_f32_e32 v0, v0
	v_mul_f32_e32 v1, 0x2f800000, v0
	v_floor_f32_e32 v1, v1
	v_fmac_f32_e32 v0, 0xcf800000, v1
	v_cvt_u32_f32_e32 v0, v0
	v_cvt_u32_f32_e32 v1, v1
	v_lshl_add_u64 v[2:3], v[16:17], 3, s[12:13]
	global_atomic_add_x2 v[2:3], v[0:1], off

; __device__ __forceinline__ float ss_scale(const u64* ss, int row) { return __builtin_amdgcn_rsqf((float)ss[row] * (1.f / 4294967296.f / 1024.f) + EPS); }
; __device__ __forceinline__ u64 ss_fix(float q) { return (u64)(q * 4294967296.f); }
;     __device__ __forceinline__ void operator()(const f32x4 (&acc)[2][2][4][2], const pg8::Unit& u, int wr, int wc, int fr, int fq) const {
;     ...
; #pragma unroll
;         for (int ai = 0; ai < 2; ++ai)
; #pragma unroll
;             for (int m = 0; m < 4; ++m) {
;                 const int row = row0 + ai * 128 + m * 16;
;                 float q = 0.f, qw = 0.f, sh = 1.f;
;                 if constexpr (MODE == 2) sh = ss_scale(rss, row);
; #pragma unroll
;                 for (int bj = 0; bj < 2; ++bj) {
;                     const int c = col0 + bj * 128;
;                     const u32x4 rb = *(const u32x4*)(hb + (size_t)row * DM + c);
;                     f32x4 r0 = {bflo(rb.x), bfhi(rb.x), bflo(rb.y), bfhi(rb.y)}, r1 = {bflo(rb.z), bfhi(rb.z), bflo(rb.w), bfhi(rb.w)};
;                     if constexpr (MODE == 2) { r0 = r0 * sh * g0[bj]; r1 = r1 * sh * g1[bj]; }
;                     const f32x4 v0 = r0 + acc[ai][bj][m][0], v1 = r1 + acc[ai][bj][m][1];
;                     if constexpr (WF32) { *(f32x4*)(out + (size_t)row * DM + c) = v0; *(f32x4*)(out + (size_t)row * DM + c + 4) = v1; }
;                     u32x4 w; w.x = pkbf(v0[0], v0[1]); w.y = pkbf(v0[2], v0[3]); w.z = pkbf(v1[0], v1[1]); w.w = pkbf(v1[2], v1[3]);
;                     *(u32x4*)(hb + (size_t)row * DM + c) = w;
;                     const f32x4 s0 = v0 * v0, s1 = v1 * v1;
;                     q += (s0[0] + s0[1]) + (s0[2] + s0[3]) + (s1[0] + s1[1]) + (s1[2] + s1[3]);
;                     if constexpr (MODE == 1) { const f32x4 t0 = s0 * g0[bj], t1 = s1 * g1[bj]; qw += (t0[0] + t0[1]) + (t0[2] + t0[3]) + (t1[0] + t1[1]) + (t1[2] + t1[3]); }
;                 }
;                 q += __shfl_xor(q, 16); q += __shfl_xor(q, 32);
;                 if constexpr (MODE == 1) { qw += __shfl_xor(qw, 16); qw += __shfl_xor(qw, 32); }
;                 if (fq == 0) {
;                     __hip_atomic_fetch_add(ssn + row, ss_fix(q), __ATOMIC_RELAXED, __HIP_MEMORY_SCOPE_AGENT);
;                     if constexpr (MODE == 1) __hip_atomic_fetch_add(ssw + row, ss_fix(qw), __ATOMIC_RELAXED, __HIP_MEMORY_SCOPE_AGENT);
;                 }
;             }
.LBB0_770:
	v_lshl_add_u32 v146, s57, 8, v148
	v_ashrrev_i32_e32 v147, 31, v146
	v_lshl_or_b32 v144, s26, 8, v149
	v_lshlrev_b64 v[156:157], 11, v[146:147]
	v_lshl_add_u64 v[156:157], s[10:11], 0, v[156:157]
	v_ashrrev_i32_e32 v145, 31, v144
	v_lshl_add_u64 v[166:167], v[144:145], 1, v[156:157]
	global_load_dwordx4 v[158:161], v[166:167], off
	global_load_dwordx4 v[162:165], v[166:167], off offset:256
	v_mov_b32_e32 v220, v166
	v_mov_b32_e32 v221, v167
	s_mov_b32 s100, 0x8000
	s_mov_b32 s101, 0
	v_lshl_add_u64 v[222:223], v[166:167], 0, s[100:101]
	global_load_dwordx4 v[184:187], v[222:223], off
	global_load_dwordx4 v[188:191], v[222:223], off offset:256
	s_mov_b32 s100, 0x10000
	s_mov_b32 s101, 0
	v_lshl_add_u64 v[222:223], v[166:167], 0, s[100:101]
	global_load_dwordx4 v[192:195], v[222:223], off
	global_load_dwordx4 v[200:203], v[222:223], off offset:256
	s_mov_b32 s100, 0x18000
	s_mov_b32 s101, 0
	v_lshl_add_u64 v[222:223], v[166:167], 0, s[100:101]
	global_load_dwordx4 v[204:207], v[222:223], off
	global_load_dwordx4 v[208:211], v[222:223], off offset:256
	s_mov_b32 s100, 0x40000
	s_mov_b32 s101, 0
	v_lshl_add_u64 v[222:223], v[166:167], 0, s[100:101]
	global_load_dwordx4 v[212:215], v[222:223], off
	global_load_dwordx4 v[216:219], v[222:223], off offset:256
	s_mov_b32 s100, 0x48000
	s_mov_b32 s101, 0
	v_lshl_add_u64 v[222:223], v[166:167], 0, s[100:101]
	global_load_dwordx4 v[176:179], v[222:223], off
	global_load_dwordx4 v[180:183], v[222:223], off offset:256
	v_and_b32_e32 v157, 64, v155
	v_xor_b32_e32 v156, 16, v155
	v_add_u32_e32 v157, 64, v157
	v_xor_b32_e32 v168, 32, v155
	v_cmp_lt_i32_e32 vcc, v156, v157
	s_waitcnt vmcnt(10)
	v_and_b32_e32 v169, 0xffff0000, v158
	v_cndmask_b32_e32 v156, v155, v156, vcc
	v_cmp_lt_i32_e32 vcc, v168, v157
	v_lshlrev_b32_e32 v157, 2, v156
	v_lshlrev_b32_e32 v170, 16, v160
	v_cndmask_b32_e32 v168, v155, v168, vcc
	v_lshlrev_b32_e32 v156, 2, v168
	v_lshlrev_b32_e32 v168, 16, v158
	v_lshlrev_b32_e32 v158, 16, v159
	v_and_b32_e32 v159, 0xffff0000, v159
	v_and_b32_e32 v171, 0xffff0000, v160
	v_lshlrev_b32_e32 v160, 16, v161
	v_and_b32_e32 v161, 0xffff0000, v161
	v_lshlrev_b32_e32 v172, 16, v162
	v_and_b32_e32 v173, 0xffff0000, v162
	v_lshlrev_b32_e32 v162, 16, v163
	v_and_b32_e32 v163, 0xffff0000, v163
	v_lshlrev_b32_e32 v174, 16, v164
	v_and_b32_e32 v175, 0xffff0000, v164
	v_lshlrev_b32_e32 v164, 16, v165
	v_and_b32_e32 v165, 0xffff0000, v165
	v_pk_add_f32 v[126:127], v[126:127], v[158:159]
	v_pk_add_f32 v[124:125], v[124:125], v[168:169]
	v_pk_add_f32 v[122:123], v[122:123], v[160:161]
	v_pk_add_f32 v[118:119], v[118:119], v[162:163]
	v_pk_add_f32 v[116:117], v[116:117], v[172:173]
	v_pk_add_f32 v[120:121], v[120:121], v[170:171]
	v_pk_add_f32 v[158:159], v[114:115], v[164:165]
	v_pk_add_f32 v[160:161], v[112:113], v[174:175]
	v_cvt_pk_bf16_f32 v112, v124, v125
	v_cvt_pk_bf16_f32 v113, v126, v127
	v_pk_mul_f32 v[114:115], v[126:127], v[126:127]
	v_pk_mul_f32 v[124:125], v[124:125], v[124:125]
	v_pk_mul_f32 v[126:127], v[122:123], v[122:123]
	v_pk_mul_f32 v[164:165], v[118:119], v[118:119]
	v_pk_mul_f32 v[168:169], v[116:117], v[116:117]
	v_pk_mul_f32 v[162:163], v[120:121], v[120:121]
	v_pk_mul_f32 v[172:173], v[160:161], v[160:161]
	v_add_f32_e32 v124, v124, v125
	v_add_f32_e32 v114, v114, v115
	v_add_f32_e32 v125, v126, v127
	v_add_f32_e32 v126, v168, v169
	v_add_f32_e32 v127, v164, v165
	v_pk_mul_f32 v[170:171], v[158:159], v[158:159]
	v_add_f32_e32 v115, v162, v163
	v_add_f32_e32 v162, v172, v173
	v_add_f32_e32 v114, v124, v114
	v_add_f32_e32 v124, v126, v127
	v_add_f32_e32 v163, v170, v171
	v_add_f32_e32 v114, v115, v114
	v_add_f32_e32 v115, v162, v124
	v_add_f32_e32 v114, v125, v114
	v_add_f32_e32 v115, v163, v115
	v_add_f32_e32 v124, v114, v115
	ds_bpermute_b32 v125, v157, v124
	v_cvt_pk_bf16_f32 v114, v120, v121
	v_cvt_pk_bf16_f32 v115, v122, v123
	global_store_dwordx4 v[166:167], v[112:115], off
	s_waitcnt lgkmcnt(0)
	s_nop 0
	v_add_f32_e32 v112, v124, v125
	ds_bpermute_b32 v113, v156, v112
	v_cvt_pk_bf16_f32 v114, v116, v117
	v_cvt_pk_bf16_f32 v115, v118, v119
	v_cvt_pk_bf16_f32 v116, v160, v161
	v_cvt_pk_bf16_f32 v117, v158, v159
	global_store_dwordx4 v[166:167], v[114:117], off offset:256
	s_and_saveexec_b64 s[6:7], s[2:3]
	s_cbranch_execz .LBB0_772
	s_waitcnt lgkmcnt(0)
	v_add_f32_e32 v112, v112, v113
	v_mul_f32_e32 v112, 0x4f800000, v112
	v_trunc_f32_e32 v112, v112
	v_mul_f32_e32 v113, 0x2f800000, v112
	v_floor_f32_e32 v113, v113
	v_fmac_f32_e32 v112, 0xcf800000, v113
	v_cvt_u32_f32_e32 v112, v112
	v_cvt_u32_f32_e32 v113, v113
	v_lshl_add_u64 v[114:115], v[146:147], 3, s[12:13]
	global_atomic_add_x2 v[114:115], v[112:113], off
; __device__ __forceinline__ float ss_scale(const u64* ss, int row) { return __builtin_amdgcn_rsqf((float)ss[row] * (1.f / 4294967296.f / 1024.f) + EPS); }
; __device__ __forceinline__ u64 ss_fix(float q) { return (u64)(q * 4294967296.f); }
;     __device__ __forceinline__ void operator()(const f32x4 (&acc)[2][2][4][2], const pg8::Unit& u, int wr, int wc, int fr, int fq) const {
;     ...
;         for (int ai = 0; ai < 2; ++ai)
; #pragma unroll
;             for (int m = 0; m < 4; ++m) {
;                 const int row = row0 + ai * 128 + m * 16;
;                 float q = 0.f, qw = 0.f, sh = 1.f;
;                 if constexpr (MODE == 2) sh = ss_scale(rss, row);
; #pragma unroll
;                 for (int bj = 0; bj < 2; ++bj) {
;                     const int c = col0 + bj * 128;
;                     const u32x4 rb = *(const u32x4*)(hb + (size_t)row * DM + c);
;                     f32x4 r0 = {bflo(rb.x), bfhi(rb.x), bflo(rb.y), bfhi(rb.y)}, r1 = {bflo(rb.z), bfhi(rb.z), bflo(rb.w), bfhi(rb.w)};
;                     if constexpr (MODE == 2) { r0 = r0 * sh * g0[bj]; r1 = r1 * sh * g1[bj]; }
;                     const f32x4 v0 = r0 + acc[ai][bj][m][0], v1 = r1 + acc[ai][bj][m][1];
;                     if constexpr (WF32) { *(f32x4*)(out + (size_t)row * DM + c) = v0; *(f32x4*)(out + (size_t)row * DM + c + 4) = v1; }
;                     u32x4 w; w.x = pkbf(v0[0], v0[1]); w.y = pkbf(v0[2], v0[3]); w.z = pkbf(v1[0], v1[1]); w.w = pkbf(v1[2], v1[3]);
;                     *(u32x4*)(hb + (size_t)row * DM + c) = w;
;                     const f32x4 s0 = v0 * v0, s1 = v1 * v1;
;                     q += (s0[0] + s0[1]) + (s0[2] + s0[3]) + (s1[0] + s1[1]) + (s1[2] + s1[3]);
;                     if constexpr (MODE == 1) { const f32x4 t0 = s0 * g0[bj], t1 = s1 * g1[bj]; qw += (t0[0] + t0[1]) + (t0[2] + t0[3]) + (t1[0] + t1[1]) + (t1[2] + t1[3]); }
;                 }
;                 q += __shfl_xor(q, 16); q += __shfl_xor(q, 32);
;                 if constexpr (MODE == 1) { qw += __shfl_xor(qw, 16); qw += __shfl_xor(qw, 32); }
;                 if (fq == 0) {
;                     __hip_atomic_fetch_add(ssn + row, ss_fix(q), __ATOMIC_RELAXED, __HIP_MEMORY_SCOPE_AGENT);
;                     if constexpr (MODE == 1) __hip_atomic_fetch_add(ssw + row, ss_fix(qw), __ATOMIC_RELAXED, __HIP_MEMORY_SCOPE_AGENT);
;                 }
;             }
.LBB0_772:
	s_or_b64 exec, exec, s[6:7]
	v_or_b32_e32 v112, 16, v146
	s_waitcnt lgkmcnt(0)
	v_ashrrev_i32_e32 v113, 31, v112
	v_lshlrev_b64 v[114:115], 11, v[112:113]
	v_lshl_add_u64 v[114:115], s[10:11], 0, v[114:115]
	v_lshl_add_u64 v[122:123], v[144:145], 1, v[114:115]
	s_nop 0
	s_nop 0
	s_waitcnt vmcnt(12)
	v_lshlrev_b32_e32 v124, 16, v184
	v_and_b32_e32 v125, 0xffff0000, v184
	v_lshlrev_b32_e32 v114, 16, v185
	v_and_b32_e32 v115, 0xffff0000, v185
	v_lshlrev_b32_e32 v126, 16, v186
	v_and_b32_e32 v127, 0xffff0000, v186
	v_lshlrev_b32_e32 v116, 16, v187
	v_and_b32_e32 v117, 0xffff0000, v187
	s_waitcnt vmcnt(11)
	v_lshlrev_b32_e32 v158, 16, v188
	v_and_b32_e32 v159, 0xffff0000, v188
	v_lshlrev_b32_e32 v118, 16, v189
	v_and_b32_e32 v119, 0xffff0000, v189
	v_lshlrev_b32_e32 v160, 16, v190
	v_and_b32_e32 v161, 0xffff0000, v190
	v_lshlrev_b32_e32 v120, 16, v191
	v_and_b32_e32 v121, 0xffff0000, v191
	s_mov_b32 s100, 0x50000
	s_mov_b32 s101, 0
	v_lshl_add_u64 v[222:223], v[220:221], 0, s[100:101]
	global_load_dwordx4 v[184:187], v[222:223], off
	global_load_dwordx4 v[188:191], v[222:223], off offset:256
	v_pk_add_f32 v[110:111], v[110:111], v[114:115]
	v_pk_add_f32 v[108:109], v[108:109], v[124:125]
	v_pk_add_f32 v[106:107], v[106:107], v[116:117]
	v_pk_add_f32 v[102:103], v[102:103], v[118:119]
	v_pk_add_f32 v[100:101], v[100:101], v[158:159]
	v_pk_add_f32 v[104:105], v[104:105], v[126:127]
	v_pk_add_f32 v[114:115], v[98:99], v[120:121]
	v_pk_add_f32 v[116:117], v[96:97], v[160:161]
	v_cvt_pk_bf16_f32 v96, v108, v109
	v_cvt_pk_bf16_f32 v97, v110, v111
	v_pk_mul_f32 v[98:99], v[110:111], v[110:111]
	v_pk_mul_f32 v[108:109], v[108:109], v[108:109]
	v_pk_mul_f32 v[110:111], v[106:107], v[106:107]
	v_pk_mul_f32 v[120:121], v[102:103], v[102:103]
	v_pk_mul_f32 v[124:125], v[100:101], v[100:101]
	v_pk_mul_f32 v[118:119], v[104:105], v[104:105]
	v_pk_mul_f32 v[158:159], v[116:117], v[116:117]
	v_add_f32_e32 v108, v108, v109
	v_add_f32_e32 v98, v98, v99
	v_add_f32_e32 v109, v110, v111
	v_add_f32_e32 v110, v124, v125
	v_add_f32_e32 v111, v120, v121
	v_pk_mul_f32 v[126:127], v[114:115], v[114:115]
	v_add_f32_e32 v99, v118, v119
	v_add_f32_e32 v118, v158, v159
	v_add_f32_e32 v98, v108, v98
	v_add_f32_e32 v108, v110, v111
	v_add_f32_e32 v119, v126, v127
	v_add_f32_e32 v98, v99, v98
	v_add_f32_e32 v99, v118, v108
	v_add_f32_e32 v98, v109, v98
	v_add_f32_e32 v99, v119, v99
	v_add_f32_e32 v108, v98, v99
	ds_bpermute_b32 v109, v157, v108
	v_cvt_pk_bf16_f32 v98, v104, v105
	v_cvt_pk_bf16_f32 v99, v106, v107
	global_store_dwordx4 v[122:123], v[96:99], off
	s_waitcnt lgkmcnt(0)
	s_nop 0
	v_add_f32_e32 v96, v108, v109
	ds_bpermute_b32 v97, v156, v96
	v_cvt_pk_bf16_f32 v98, v100, v101
	v_cvt_pk_bf16_f32 v99, v102, v103
	v_cvt_pk_bf16_f32 v100, v116, v117
	v_cvt_pk_bf16_f32 v101, v114, v115
	global_store_dwordx4 v[122:123], v[98:101], off offset:256
	s_and_saveexec_b64 s[6:7], s[2:3]
	s_cbranch_execz .LBB0_774
	s_waitcnt lgkmcnt(0)
	v_add_f32_e32 v96, v96, v97
	v_mul_f32_e32 v96, 0x4f800000, v96
	v_trunc_f32_e32 v96, v96
	v_mul_f32_e32 v97, 0x2f800000, v96
	v_floor_f32_e32 v97, v97
	v_fmac_f32_e32 v96, 0xcf800000, v97
	v_cvt_u32_f32_e32 v96, v96
	v_cvt_u32_f32_e32 v97, v97
	v_lshl_add_u64 v[98:99], v[112:113], 3, s[12:13]
	global_atomic_add_x2 v[98:99], v[96:97], off
.LBB0_774:
	s_or_b64 exec, exec, s[6:7]
	v_or_b32_e32 v96, 32, v146
	s_waitcnt lgkmcnt(0)
	v_ashrrev_i32_e32 v97, 31, v96
	v_lshlrev_b64 v[98:99], 11, v[96:97]
	v_lshl_add_u64 v[98:99], s[10:11], 0, v[98:99]
	v_lshl_add_u64 v[106:107], v[144:145], 1, v[98:99]
	s_nop 0
	s_nop 0
	s_waitcnt vmcnt(15)
	v_lshlrev_b32_e32 v108, 16, v192
	v_and_b32_e32 v109, 0xffff0000, v192
	v_lshlrev_b32_e32 v98, 16, v193
	v_and_b32_e32 v99, 0xffff0000, v193
	v_lshlrev_b32_e32 v110, 16, v194
	v_and_b32_e32 v111, 0xffff0000, v194
	v_lshlrev_b32_e32 v100, 16, v195
	v_and_b32_e32 v101, 0xffff0000, v195
	s_waitcnt vmcnt(14)
	v_lshlrev_b32_e32 v112, 16, v200
	v_and_b32_e32 v113, 0xffff0000, v200
	v_lshlrev_b32_e32 v102, 16, v201
	v_and_b32_e32 v103, 0xffff0000, v201
	v_lshlrev_b32_e32 v114, 16, v202
	v_and_b32_e32 v115, 0xffff0000, v202
	v_lshlrev_b32_e32 v104, 16, v203
	v_and_b32_e32 v105, 0xffff0000, v203
	s_mov_b32 s100, 0x58000
	s_mov_b32 s101, 0
	v_lshl_add_u64 v[222:223], v[220:221], 0, s[100:101]
	global_load_dwordx4 v[192:195], v[222:223], off
	global_load_dwordx4 v[200:203], v[222:223], off offset:256
	v_pk_add_f32 v[94:95], v[94:95], v[98:99]
	v_pk_add_f32 v[92:93], v[92:93], v[108:109]
	v_pk_add_f32 v[90:91], v[90:91], v[100:101]
	v_pk_add_f32 v[86:87], v[86:87], v[102:103]
	v_pk_add_f32 v[84:85], v[84:85], v[112:113]
	v_pk_add_f32 v[88:89], v[88:89], v[110:111]
	v_pk_add_f32 v[98:99], v[82:83], v[104:105]
	v_pk_add_f32 v[100:101], v[80:81], v[114:115]
	v_cvt_pk_bf16_f32 v80, v92, v93
	v_cvt_pk_bf16_f32 v81, v94, v95
	v_pk_mul_f32 v[82:83], v[94:95], v[94:95]
	v_pk_mul_f32 v[92:93], v[92:93], v[92:93]
	v_pk_mul_f32 v[94:95], v[90:91], v[90:91]
	v_pk_mul_f32 v[104:105], v[86:87], v[86:87]
	v_pk_mul_f32 v[108:109], v[84:85], v[84:85]
	v_pk_mul_f32 v[102:103], v[88:89], v[88:89]
	v_pk_mul_f32 v[112:113], v[100:101], v[100:101]
	v_add_f32_e32 v92, v92, v93
	v_add_f32_e32 v82, v82, v83
	v_add_f32_e32 v93, v94, v95
	v_add_f32_e32 v94, v108, v109
	v_add_f32_e32 v95, v104, v105
	v_pk_mul_f32 v[110:111], v[98:99], v[98:99]
	v_add_f32_e32 v83, v102, v103
	v_add_f32_e32 v102, v112, v113
	v_add_f32_e32 v82, v92, v82
	v_add_f32_e32 v92, v94, v95
	v_add_f32_e32 v103, v110, v111
	v_add_f32_e32 v82, v83, v82
	v_add_f32_e32 v83, v102, v92
	v_add_f32_e32 v82, v93, v82
	v_add_f32_e32 v83, v103, v83
	v_add_f32_e32 v92, v82, v83
	ds_bpermute_b32 v93, v157, v92
	v_cvt_pk_bf16_f32 v82, v88, v89
	v_cvt_pk_bf16_f32 v83, v90, v91
	global_store_dwordx4 v[106:107], v[80:83], off
	s_waitcnt lgkmcnt(0)
	s_nop 0
	v_add_f32_e32 v80, v92, v93
	ds_bpermute_b32 v81, v156, v80
	v_cvt_pk_bf16_f32 v82, v84, v85
	v_cvt_pk_bf16_f32 v83, v86, v87
	v_cvt_pk_bf16_f32 v84, v100, v101
	v_cvt_pk_bf16_f32 v85, v98, v99
	global_store_dwordx4 v[106:107], v[82:85], off offset:256
	s_and_saveexec_b64 s[6:7], s[2:3]
	s_cbranch_execz .LBB0_776
	s_waitcnt lgkmcnt(0)
	v_add_f32_e32 v80, v80, v81
	v_mul_f32_e32 v80, 0x4f800000, v80
	v_trunc_f32_e32 v80, v80
	v_mul_f32_e32 v81, 0x2f800000, v80
	v_floor_f32_e32 v81, v81
	v_fmac_f32_e32 v80, 0xcf800000, v81
	v_cvt_u32_f32_e32 v80, v80
	v_cvt_u32_f32_e32 v81, v81
	v_lshl_add_u64 v[82:83], v[96:97], 3, s[12:13]
	global_atomic_add_x2 v[82:83], v[80:81], off
; __device__ __forceinline__ float ss_scale(const u64* ss, int row) { return __builtin_amdgcn_rsqf((float)ss[row] * (1.f / 4294967296.f / 1024.f) + EPS); }
; __device__ __forceinline__ u64 ss_fix(float q) { return (u64)(q * 4294967296.f); }
;     __device__ __forceinline__ void operator()(const f32x4 (&acc)[2][2][4][2], const pg8::Unit& u, int wr, int wc, int fr, int fq) const {
;     ...
;         for (int ai = 0; ai < 2; ++ai)
; #pragma unroll
;             for (int m = 0; m < 4; ++m) {
;                 const int row = row0 + ai * 128 + m * 16;
;                 float q = 0.f, qw = 0.f, sh = 1.f;
;                 if constexpr (MODE == 2) sh = ss_scale(rss, row);
; #pragma unroll
;                 for (int bj = 0; bj < 2; ++bj) {
;                     const int c = col0 + bj * 128;
;                     const u32x4 rb = *(const u32x4*)(hb + (size_t)row * DM + c);
;                     f32x4 r0 = {bflo(rb.x), bfhi(rb.x), bflo(rb.y), bfhi(rb.y)}, r1 = {bflo(rb.z), bfhi(rb.z), bflo(rb.w), bfhi(rb.w)};
;                     if constexpr (MODE == 2) { r0 = r0 * sh * g0[bj]; r1 = r1 * sh * g1[bj]; }
;                     const f32x4 v0 = r0 + acc[ai][bj][m][0], v1 = r1 + acc[ai][bj][m][1];
;                     if constexpr (WF32) { *(f32x4*)(out + (size_t)row * DM + c) = v0; *(f32x4*)(out + (size_t)row * DM + c + 4) = v1; }
;                     u32x4 w; w.x = pkbf(v0[0], v0[1]); w.y = pkbf(v0[2], v0[3]); w.z = pkbf(v1[0], v1[1]); w.w = pkbf(v1[2], v1[3]);
;                     *(u32x4*)(hb + (size_t)row * DM + c) = w;
;                     const f32x4 s0 = v0 * v0, s1 = v1 * v1;
;                     q += (s0[0] + s0[1]) + (s0[2] + s0[3]) + (s1[0] + s1[1]) + (s1[2] + s1[3]);
;                     if constexpr (MODE == 1) { const f32x4 t0 = s0 * g0[bj], t1 = s1 * g1[bj]; qw += (t0[0] + t0[1]) + (t0[2] + t0[3]) + (t1[0] + t1[1]) + (t1[2] + t1[3]); }
;                 }
;                 q += __shfl_xor(q, 16); q += __shfl_xor(q, 32);
;                 if constexpr (MODE == 1) { qw += __shfl_xor(qw, 16); qw += __shfl_xor(qw, 32); }
;                 if (fq == 0) {
;                     __hip_atomic_fetch_add(ssn + row, ss_fix(q), __ATOMIC_RELAXED, __HIP_MEMORY_SCOPE_AGENT);
;                     if constexpr (MODE == 1) __hip_atomic_fetch_add(ssw + row, ss_fix(qw), __ATOMIC_RELAXED, __HIP_MEMORY_SCOPE_AGENT);
;                 }
;             }
.LBB0_776:
	s_or_b64 exec, exec, s[6:7]
	v_or_b32_e32 v80, 48, v146
	s_waitcnt lgkmcnt(0)
	v_ashrrev_i32_e32 v81, 31, v80
	v_lshlrev_b64 v[82:83], 11, v[80:81]
	v_lshl_add_u64 v[82:83], s[10:11], 0, v[82:83]
	v_lshl_add_u64 v[90:91], v[144:145], 1, v[82:83]
	s_nop 0
	s_nop 0
	s_waitcnt vmcnt(18)
	v_lshlrev_b32_e32 v92, 16, v204
	v_and_b32_e32 v93, 0xffff0000, v204
	v_lshlrev_b32_e32 v82, 16, v205
	v_and_b32_e32 v83, 0xffff0000, v205
	v_lshlrev_b32_e32 v94, 16, v206
	v_and_b32_e32 v95, 0xffff0000, v206
	v_lshlrev_b32_e32 v84, 16, v207
	v_and_b32_e32 v85, 0xffff0000, v207
	s_waitcnt vmcnt(17)
	v_lshlrev_b32_e32 v96, 16, v208
	v_and_b32_e32 v97, 0xffff0000, v208
	v_lshlrev_b32_e32 v86, 16, v209
	v_and_b32_e32 v87, 0xffff0000, v209
	v_lshlrev_b32_e32 v98, 16, v210
	v_and_b32_e32 v99, 0xffff0000, v210
	v_lshlrev_b32_e32 v88, 16, v211
	v_and_b32_e32 v89, 0xffff0000, v211
	v_pk_add_f32 v[78:79], v[78:79], v[82:83]
	v_pk_add_f32 v[76:77], v[76:77], v[92:93]
	v_pk_add_f32 v[74:75], v[74:75], v[84:85]
	v_pk_add_f32 v[70:71], v[70:71], v[86:87]
	v_pk_add_f32 v[68:69], v[68:69], v[96:97]
	v_pk_add_f32 v[72:73], v[72:73], v[94:95]
	v_pk_add_f32 v[82:83], v[66:67], v[88:89]
	v_pk_add_f32 v[84:85], v[64:65], v[98:99]
	v_cvt_pk_bf16_f32 v64, v76, v77
	v_cvt_pk_bf16_f32 v65, v78, v79
	v_pk_mul_f32 v[66:67], v[78:79], v[78:79]
	v_pk_mul_f32 v[76:77], v[76:77], v[76:77]
	v_pk_mul_f32 v[78:79], v[74:75], v[74:75]
	v_pk_mul_f32 v[88:89], v[70:71], v[70:71]
	v_pk_mul_f32 v[92:93], v[68:69], v[68:69]
	v_pk_mul_f32 v[86:87], v[72:73], v[72:73]
	v_pk_mul_f32 v[96:97], v[84:85], v[84:85]
	v_add_f32_e32 v76, v76, v77
	v_add_f32_e32 v66, v66, v67
	v_add_f32_e32 v77, v78, v79
	v_add_f32_e32 v78, v92, v93
	v_add_f32_e32 v79, v88, v89
	v_pk_mul_f32 v[94:95], v[82:83], v[82:83]
	v_add_f32_e32 v67, v86, v87
	v_add_f32_e32 v86, v96, v97
	v_add_f32_e32 v66, v76, v66
	v_add_f32_e32 v76, v78, v79
	v_add_f32_e32 v87, v94, v95
	v_add_f32_e32 v66, v67, v66
	v_add_f32_e32 v67, v86, v76
	v_add_f32_e32 v66, v77, v66
	v_add_f32_e32 v67, v87, v67
	v_add_f32_e32 v76, v66, v67
	ds_bpermute_b32 v77, v157, v76
	v_cvt_pk_bf16_f32 v66, v72, v73
	v_cvt_pk_bf16_f32 v67, v74, v75
	global_store_dwordx4 v[90:91], v[64:67], off
	s_waitcnt lgkmcnt(0)
	s_nop 0
	v_add_f32_e32 v64, v76, v77
	ds_bpermute_b32 v65, v156, v64
	v_cvt_pk_bf16_f32 v66, v68, v69
	v_cvt_pk_bf16_f32 v67, v70, v71
	v_cvt_pk_bf16_f32 v68, v84, v85
	v_cvt_pk_bf16_f32 v69, v82, v83
	global_store_dwordx4 v[90:91], v[66:69], off offset:256
	s_and_saveexec_b64 s[6:7], s[2:3]
	s_cbranch_execz .LBB0_778
	s_waitcnt lgkmcnt(0)
	v_add_f32_e32 v64, v64, v65
	v_mul_f32_e32 v64, 0x4f800000, v64
	v_trunc_f32_e32 v64, v64
	v_mul_f32_e32 v65, 0x2f800000, v64
	v_floor_f32_e32 v65, v65
	v_fmac_f32_e32 v64, 0xcf800000, v65
	v_cvt_u32_f32_e32 v64, v64
	v_cvt_u32_f32_e32 v65, v65
	v_lshl_add_u64 v[66:67], v[80:81], 3, s[12:13]
	global_atomic_add_x2 v[66:67], v[64:65], off
.LBB0_778:
	s_or_b64 exec, exec, s[6:7]
	v_add_u32_e32 v64, 0x80, v146
	s_waitcnt lgkmcnt(0)
	v_ashrrev_i32_e32 v65, 31, v64
	v_lshlrev_b64 v[66:67], 11, v[64:65]
	v_lshl_add_u64 v[66:67], s[10:11], 0, v[66:67]
	v_lshl_add_u64 v[74:75], v[144:145], 1, v[66:67]
	s_nop 0
	s_nop 0
	s_waitcnt vmcnt(19)
	v_lshlrev_b32_e32 v76, 16, v212
	v_and_b32_e32 v77, 0xffff0000, v212
	v_lshlrev_b32_e32 v66, 16, v213
	v_and_b32_e32 v67, 0xffff0000, v213
	v_lshlrev_b32_e32 v78, 16, v214
	v_and_b32_e32 v79, 0xffff0000, v214
	v_lshlrev_b32_e32 v68, 16, v215
	v_and_b32_e32 v69, 0xffff0000, v215
	s_waitcnt vmcnt(18)
	v_lshlrev_b32_e32 v80, 16, v216
	v_and_b32_e32 v81, 0xffff0000, v216
	v_lshlrev_b32_e32 v70, 16, v217
	v_and_b32_e32 v71, 0xffff0000, v217
	v_lshlrev_b32_e32 v82, 16, v218
	v_and_b32_e32 v83, 0xffff0000, v218
	v_lshlrev_b32_e32 v72, 16, v219
	v_and_b32_e32 v73, 0xffff0000, v219
	v_pk_add_f32 v[62:63], v[62:63], v[66:67]
	v_pk_add_f32 v[60:61], v[60:61], v[76:77]
	v_pk_add_f32 v[58:59], v[58:59], v[68:69]
	v_pk_add_f32 v[54:55], v[54:55], v[70:71]
	v_pk_add_f32 v[52:53], v[52:53], v[80:81]
	v_pk_add_f32 v[56:57], v[56:57], v[78:79]
	v_pk_add_f32 v[66:67], v[50:51], v[72:73]
	v_pk_add_f32 v[68:69], v[48:49], v[82:83]
	v_cvt_pk_bf16_f32 v48, v60, v61
	v_cvt_pk_bf16_f32 v49, v62, v63
	v_pk_mul_f32 v[50:51], v[62:63], v[62:63]
	v_pk_mul_f32 v[60:61], v[60:61], v[60:61]
	v_pk_mul_f32 v[62:63], v[58:59], v[58:59]
	v_pk_mul_f32 v[72:73], v[54:55], v[54:55]
	v_pk_mul_f32 v[76:77], v[52:53], v[52:53]
	v_pk_mul_f32 v[70:71], v[56:57], v[56:57]
	v_pk_mul_f32 v[80:81], v[68:69], v[68:69]
	v_add_f32_e32 v60, v60, v61
	v_add_f32_e32 v50, v50, v51
	v_add_f32_e32 v61, v62, v63
	v_add_f32_e32 v62, v76, v77
	v_add_f32_e32 v63, v72, v73
	v_pk_mul_f32 v[78:79], v[66:67], v[66:67]
	v_add_f32_e32 v51, v70, v71
	v_add_f32_e32 v70, v80, v81
	v_add_f32_e32 v50, v60, v50
	v_add_f32_e32 v60, v62, v63
	v_add_f32_e32 v71, v78, v79
	v_add_f32_e32 v50, v51, v50
	v_add_f32_e32 v51, v70, v60
	v_add_f32_e32 v50, v61, v50
	v_add_f32_e32 v51, v71, v51
	v_add_f32_e32 v60, v50, v51
	ds_bpermute_b32 v61, v157, v60
	v_cvt_pk_bf16_f32 v50, v56, v57
	v_cvt_pk_bf16_f32 v51, v58, v59
	global_store_dwordx4 v[74:75], v[48:51], off
	s_waitcnt lgkmcnt(0)
	s_nop 0
	v_add_f32_e32 v48, v60, v61
	ds_bpermute_b32 v49, v156, v48
	v_cvt_pk_bf16_f32 v50, v52, v53
	v_cvt_pk_bf16_f32 v51, v54, v55
	v_cvt_pk_bf16_f32 v52, v68, v69
	v_cvt_pk_bf16_f32 v53, v66, v67
	global_store_dwordx4 v[74:75], v[50:53], off offset:256
	s_and_saveexec_b64 s[6:7], s[2:3]
	s_cbranch_execz .LBB0_780
	s_waitcnt lgkmcnt(0)
	v_add_f32_e32 v48, v48, v49
	v_mul_f32_e32 v48, 0x4f800000, v48
	v_trunc_f32_e32 v48, v48
	v_mul_f32_e32 v49, 0x2f800000, v48
	v_floor_f32_e32 v49, v49
	v_fmac_f32_e32 v48, 0xcf800000, v49
	v_cvt_u32_f32_e32 v48, v48
	v_cvt_u32_f32_e32 v49, v49
	v_lshl_add_u64 v[50:51], v[64:65], 3, s[12:13]
	global_atomic_add_x2 v[50:51], v[48:49], off
; __device__ __forceinline__ float ss_scale(const u64* ss, int row) { return __builtin_amdgcn_rsqf((float)ss[row] * (1.f / 4294967296.f / 1024.f) + EPS); }
; __device__ __forceinline__ u64 ss_fix(float q) { return (u64)(q * 4294967296.f); }
;     __device__ __forceinline__ void operator()(const f32x4 (&acc)[2][2][4][2], const pg8::Unit& u, int wr, int wc, int fr, int fq) const {
;     ...
;         for (int ai = 0; ai < 2; ++ai)
; #pragma unroll
;             for (int m = 0; m < 4; ++m) {
;                 const int row = row0 + ai * 128 + m * 16;
;                 float q = 0.f, qw = 0.f, sh = 1.f;
;                 if constexpr (MODE == 2) sh = ss_scale(rss, row);
; #pragma unroll
;                 for (int bj = 0; bj < 2; ++bj) {
;                     const int c = col0 + bj * 128;
;                     const u32x4 rb = *(const u32x4*)(hb + (size_t)row * DM + c);
;                     f32x4 r0 = {bflo(rb.x), bfhi(rb.x), bflo(rb.y), bfhi(rb.y)}, r1 = {bflo(rb.z), bfhi(rb.z), bflo(rb.w), bfhi(rb.w)};
;                     if constexpr (MODE == 2) { r0 = r0 * sh * g0[bj]; r1 = r1 * sh * g1[bj]; }
;                     const f32x4 v0 = r0 + acc[ai][bj][m][0], v1 = r1 + acc[ai][bj][m][1];
;                     if constexpr (WF32) { *(f32x4*)(out + (size_t)row * DM + c) = v0; *(f32x4*)(out + (size_t)row * DM + c + 4) = v1; }
;                     u32x4 w; w.x = pkbf(v0[0], v0[1]); w.y = pkbf(v0[2], v0[3]); w.z = pkbf(v1[0], v1[1]); w.w = pkbf(v1[2], v1[3]);
;                     *(u32x4*)(hb + (size_t)row * DM + c) = w;
;                     const f32x4 s0 = v0 * v0, s1 = v1 * v1;
;                     q += (s0[0] + s0[1]) + (s0[2] + s0[3]) + (s1[0] + s1[1]) + (s1[2] + s1[3]);
;                     if constexpr (MODE == 1) { const f32x4 t0 = s0 * g0[bj], t1 = s1 * g1[bj]; qw += (t0[0] + t0[1]) + (t0[2] + t0[3]) + (t1[0] + t1[1]) + (t1[2] + t1[3]); }
;                 }
;                 q += __shfl_xor(q, 16); q += __shfl_xor(q, 32);
;                 if constexpr (MODE == 1) { qw += __shfl_xor(qw, 16); qw += __shfl_xor(qw, 32); }
;                 if (fq == 0) {
;                     __hip_atomic_fetch_add(ssn + row, ss_fix(q), __ATOMIC_RELAXED, __HIP_MEMORY_SCOPE_AGENT);
;                     if constexpr (MODE == 1) __hip_atomic_fetch_add(ssw + row, ss_fix(qw), __ATOMIC_RELAXED, __HIP_MEMORY_SCOPE_AGENT);
;                 }
;             }
.LBB0_780:
	s_or_b64 exec, exec, s[6:7]
	v_add_u32_e32 v48, 0x90, v146
	s_waitcnt lgkmcnt(0)
	v_ashrrev_i32_e32 v49, 31, v48
	v_lshlrev_b64 v[50:51], 11, v[48:49]
	v_lshl_add_u64 v[50:51], s[10:11], 0, v[50:51]
	v_lshl_add_u64 v[58:59], v[144:145], 1, v[50:51]
	s_nop 0
	s_nop 0
	s_waitcnt vmcnt(20)
	v_lshlrev_b32_e32 v60, 16, v176
	v_and_b32_e32 v61, 0xffff0000, v176
	v_lshlrev_b32_e32 v50, 16, v177
	v_and_b32_e32 v51, 0xffff0000, v177
	v_lshlrev_b32_e32 v62, 16, v178
	v_and_b32_e32 v63, 0xffff0000, v178
	v_lshlrev_b32_e32 v52, 16, v179
	v_and_b32_e32 v53, 0xffff0000, v179
	s_waitcnt vmcnt(19)
	v_lshlrev_b32_e32 v64, 16, v180
	v_and_b32_e32 v65, 0xffff0000, v180
	v_lshlrev_b32_e32 v54, 16, v181
	v_and_b32_e32 v55, 0xffff0000, v181
	v_lshlrev_b32_e32 v66, 16, v182
	v_and_b32_e32 v67, 0xffff0000, v182
	v_lshlrev_b32_e32 v56, 16, v183
	v_and_b32_e32 v57, 0xffff0000, v183
	v_pk_add_f32 v[46:47], v[46:47], v[50:51]
	v_pk_add_f32 v[44:45], v[44:45], v[60:61]
	v_pk_add_f32 v[42:43], v[42:43], v[52:53]
	v_pk_add_f32 v[38:39], v[38:39], v[54:55]
	v_pk_add_f32 v[36:37], v[36:37], v[64:65]
	v_pk_add_f32 v[40:41], v[40:41], v[62:63]
	v_pk_add_f32 v[50:51], v[34:35], v[56:57]
	v_pk_add_f32 v[52:53], v[32:33], v[66:67]
	v_cvt_pk_bf16_f32 v32, v44, v45
	v_cvt_pk_bf16_f32 v33, v46, v47
	v_pk_mul_f32 v[34:35], v[46:47], v[46:47]
	v_pk_mul_f32 v[44:45], v[44:45], v[44:45]
	v_pk_mul_f32 v[46:47], v[42:43], v[42:43]
	v_pk_mul_f32 v[56:57], v[38:39], v[38:39]
	v_pk_mul_f32 v[60:61], v[36:37], v[36:37]
	v_pk_mul_f32 v[54:55], v[40:41], v[40:41]
	v_pk_mul_f32 v[64:65], v[52:53], v[52:53]
	v_add_f32_e32 v44, v44, v45
	v_add_f32_e32 v34, v34, v35
	v_add_f32_e32 v45, v46, v47
	v_add_f32_e32 v46, v60, v61
	v_add_f32_e32 v47, v56, v57
	v_pk_mul_f32 v[62:63], v[50:51], v[50:51]
	v_add_f32_e32 v35, v54, v55
	v_add_f32_e32 v54, v64, v65
	v_add_f32_e32 v34, v44, v34
	v_add_f32_e32 v44, v46, v47
	v_add_f32_e32 v55, v62, v63
	v_add_f32_e32 v34, v35, v34
	v_add_f32_e32 v35, v54, v44
	v_add_f32_e32 v34, v45, v34
	v_add_f32_e32 v35, v55, v35
	v_add_f32_e32 v44, v34, v35
	ds_bpermute_b32 v45, v157, v44
	v_cvt_pk_bf16_f32 v34, v40, v41
	v_cvt_pk_bf16_f32 v35, v42, v43
	global_store_dwordx4 v[58:59], v[32:35], off
	s_waitcnt lgkmcnt(0)
	s_nop 0
	v_add_f32_e32 v32, v44, v45
	ds_bpermute_b32 v33, v156, v32
	v_cvt_pk_bf16_f32 v34, v36, v37
	v_cvt_pk_bf16_f32 v35, v38, v39
	v_cvt_pk_bf16_f32 v36, v52, v53
	v_cvt_pk_bf16_f32 v37, v50, v51
	global_store_dwordx4 v[58:59], v[34:37], off offset:256
	s_and_saveexec_b64 s[6:7], s[2:3]
	s_cbranch_execz .LBB0_782
	s_waitcnt lgkmcnt(0)
	v_add_f32_e32 v32, v32, v33
	v_mul_f32_e32 v32, 0x4f800000, v32
	v_trunc_f32_e32 v32, v32
	v_mul_f32_e32 v33, 0x2f800000, v32
	v_floor_f32_e32 v33, v33
	v_fmac_f32_e32 v32, 0xcf800000, v33
	v_cvt_u32_f32_e32 v32, v32
	v_cvt_u32_f32_e32 v33, v33
	v_lshl_add_u64 v[34:35], v[48:49], 3, s[12:13]
	global_atomic_add_x2 v[34:35], v[32:33], off
; __device__ __forceinline__ float ss_scale(const u64* ss, int row) { return __builtin_amdgcn_rsqf((float)ss[row] * (1.f / 4294967296.f / 1024.f) + EPS); }
; __device__ __forceinline__ u64 ss_fix(float q) { return (u64)(q * 4294967296.f); }
;     __device__ __forceinline__ void operator()(const f32x4 (&acc)[2][2][4][2], const pg8::Unit& u, int wr, int wc, int fr, int fq) const {
;     ...
;         for (int ai = 0; ai < 2; ++ai)
; #pragma unroll
;             for (int m = 0; m < 4; ++m) {
;                 const int row = row0 + ai * 128 + m * 16;
;                 float q = 0.f, qw = 0.f, sh = 1.f;
;                 if constexpr (MODE == 2) sh = ss_scale(rss, row);
; #pragma unroll
;                 for (int bj = 0; bj < 2; ++bj) {
;                     const int c = col0 + bj * 128;
;                     const u32x4 rb = *(const u32x4*)(hb + (size_t)row * DM + c);
;                     f32x4 r0 = {bflo(rb.x), bfhi(rb.x), bflo(rb.y), bfhi(rb.y)}, r1 = {bflo(rb.z), bfhi(rb.z), bflo(rb.w), bfhi(rb.w)};
;                     if constexpr (MODE == 2) { r0 = r0 * sh * g0[bj]; r1 = r1 * sh * g1[bj]; }
;                     const f32x4 v0 = r0 + acc[ai][bj][m][0], v1 = r1 + acc[ai][bj][m][1];
;                     if constexpr (WF32) { *(f32x4*)(out + (size_t)row * DM + c) = v0; *(f32x4*)(out + (size_t)row * DM + c + 4) = v1; }
;                     u32x4 w; w.x = pkbf(v0[0], v0[1]); w.y = pkbf(v0[2], v0[3]); w.z = pkbf(v1[0], v1[1]); w.w = pkbf(v1[2], v1[3]);
;                     *(u32x4*)(hb + (size_t)row * DM + c) = w;
;                     const f32x4 s0 = v0 * v0, s1 = v1 * v1;
;                     q += (s0[0] + s0[1]) + (s0[2] + s0[3]) + (s1[0] + s1[1]) + (s1[2] + s1[3]);
;                     if constexpr (MODE == 1) { const f32x4 t0 = s0 * g0[bj], t1 = s1 * g1[bj]; qw += (t0[0] + t0[1]) + (t0[2] + t0[3]) + (t1[0] + t1[1]) + (t1[2] + t1[3]); }
;                 }
;                 q += __shfl_xor(q, 16); q += __shfl_xor(q, 32);
;                 if constexpr (MODE == 1) { qw += __shfl_xor(qw, 16); qw += __shfl_xor(qw, 32); }
;                 if (fq == 0) {
;                     __hip_atomic_fetch_add(ssn + row, ss_fix(q), __ATOMIC_RELAXED, __HIP_MEMORY_SCOPE_AGENT);
;                     if constexpr (MODE == 1) __hip_atomic_fetch_add(ssw + row, ss_fix(qw), __ATOMIC_RELAXED, __HIP_MEMORY_SCOPE_AGENT);
;                 }
;             }
.LBB0_782:
	s_or_b64 exec, exec, s[6:7]
	v_add_u32_e32 v32, 0xa0, v146
	s_waitcnt lgkmcnt(0)
	v_ashrrev_i32_e32 v33, 31, v32
	v_lshlrev_b64 v[34:35], 11, v[32:33]
	v_lshl_add_u64 v[34:35], s[10:11], 0, v[34:35]
	v_lshl_add_u64 v[42:43], v[144:145], 1, v[34:35]
	s_nop 0
	s_nop 0
	s_waitcnt vmcnt(18)
	v_lshlrev_b32_e32 v44, 16, v184
	v_and_b32_e32 v45, 0xffff0000, v184
	v_lshlrev_b32_e32 v34, 16, v185
	v_and_b32_e32 v35, 0xffff0000, v185
	v_lshlrev_b32_e32 v46, 16, v186
	v_and_b32_e32 v47, 0xffff0000, v186
	v_lshlrev_b32_e32 v36, 16, v187
	v_and_b32_e32 v37, 0xffff0000, v187
	s_waitcnt vmcnt(17)
	v_lshlrev_b32_e32 v48, 16, v188
	v_and_b32_e32 v49, 0xffff0000, v188
	v_lshlrev_b32_e32 v38, 16, v189
	v_and_b32_e32 v39, 0xffff0000, v189
	v_lshlrev_b32_e32 v50, 16, v190
	v_and_b32_e32 v51, 0xffff0000, v190
	v_lshlrev_b32_e32 v40, 16, v191
	v_and_b32_e32 v41, 0xffff0000, v191
	v_pk_add_f32 v[30:31], v[30:31], v[34:35]
	v_pk_add_f32 v[28:29], v[28:29], v[44:45]
	v_pk_add_f32 v[26:27], v[26:27], v[36:37]
	v_pk_add_f32 v[22:23], v[22:23], v[38:39]
	v_pk_add_f32 v[20:21], v[20:21], v[48:49]
	v_pk_add_f32 v[24:25], v[24:25], v[46:47]
	v_pk_add_f32 v[34:35], v[18:19], v[40:41]
	v_pk_add_f32 v[36:37], v[16:17], v[50:51]
	v_cvt_pk_bf16_f32 v16, v28, v29
	v_cvt_pk_bf16_f32 v17, v30, v31
	v_pk_mul_f32 v[18:19], v[30:31], v[30:31]
	v_pk_mul_f32 v[28:29], v[28:29], v[28:29]
	v_pk_mul_f32 v[30:31], v[26:27], v[26:27]
	v_pk_mul_f32 v[40:41], v[22:23], v[22:23]
	v_pk_mul_f32 v[44:45], v[20:21], v[20:21]
	v_pk_mul_f32 v[38:39], v[24:25], v[24:25]
	v_pk_mul_f32 v[48:49], v[36:37], v[36:37]
	v_add_f32_e32 v28, v28, v29
	v_add_f32_e32 v18, v18, v19
	v_add_f32_e32 v29, v30, v31
	v_add_f32_e32 v30, v44, v45
	v_add_f32_e32 v31, v40, v41
	v_pk_mul_f32 v[46:47], v[34:35], v[34:35]
	v_add_f32_e32 v19, v38, v39
	v_add_f32_e32 v38, v48, v49
	v_add_f32_e32 v18, v28, v18
	v_add_f32_e32 v28, v30, v31
	v_add_f32_e32 v39, v46, v47
	v_add_f32_e32 v18, v19, v18
	v_add_f32_e32 v19, v38, v28
	v_add_f32_e32 v18, v29, v18
	v_add_f32_e32 v19, v39, v19
	v_add_f32_e32 v28, v18, v19
	ds_bpermute_b32 v29, v157, v28
	v_cvt_pk_bf16_f32 v18, v24, v25
	v_cvt_pk_bf16_f32 v19, v26, v27
	global_store_dwordx4 v[42:43], v[16:19], off
	s_waitcnt lgkmcnt(0)
	s_nop 0
	v_add_f32_e32 v16, v28, v29
	ds_bpermute_b32 v17, v156, v16
	v_cvt_pk_bf16_f32 v18, v20, v21
	v_cvt_pk_bf16_f32 v19, v22, v23
	v_cvt_pk_bf16_f32 v20, v36, v37
	v_cvt_pk_bf16_f32 v21, v34, v35
	global_store_dwordx4 v[42:43], v[18:21], off offset:256
	s_and_saveexec_b64 s[6:7], s[2:3]
	s_cbranch_execz .LBB0_784
	s_waitcnt lgkmcnt(0)
	v_add_f32_e32 v16, v16, v17
	v_mul_f32_e32 v16, 0x4f800000, v16
	v_trunc_f32_e32 v16, v16
	v_mul_f32_e32 v17, 0x2f800000, v16
	v_floor_f32_e32 v17, v17
	v_fmac_f32_e32 v16, 0xcf800000, v17
	v_cvt_u32_f32_e32 v16, v16
	v_cvt_u32_f32_e32 v17, v17
	v_lshl_add_u64 v[18:19], v[32:33], 3, s[12:13]
	global_atomic_add_x2 v[18:19], v[16:17], off
.LBB0_784:
	s_or_b64 exec, exec, s[6:7]
	v_add_u32_e32 v16, 0xb0, v146
	s_waitcnt lgkmcnt(0)
	v_ashrrev_i32_e32 v17, 31, v16
	v_lshlrev_b64 v[18:19], 11, v[16:17]
	v_lshl_add_u64 v[18:19], s[10:11], 0, v[18:19]
	v_lshl_add_u64 v[26:27], v[144:145], 1, v[18:19]
	s_nop 0
	s_nop 0
	s_waitcnt vmcnt(16)
	v_lshlrev_b32_e32 v28, 16, v192
	v_and_b32_e32 v29, 0xffff0000, v192
	v_lshlrev_b32_e32 v18, 16, v193
	v_and_b32_e32 v19, 0xffff0000, v193
	v_lshlrev_b32_e32 v30, 16, v194
	v_and_b32_e32 v31, 0xffff0000, v194
	v_lshlrev_b32_e32 v20, 16, v195
	v_and_b32_e32 v21, 0xffff0000, v195
	s_waitcnt vmcnt(15)
	v_lshlrev_b32_e32 v32, 16, v200
	v_and_b32_e32 v33, 0xffff0000, v200
	v_lshlrev_b32_e32 v22, 16, v201
	v_and_b32_e32 v23, 0xffff0000, v201
	v_lshlrev_b32_e32 v34, 16, v202
	v_and_b32_e32 v35, 0xffff0000, v202
	v_lshlrev_b32_e32 v24, 16, v203
	v_and_b32_e32 v25, 0xffff0000, v203
	v_pk_add_f32 v[14:15], v[14:15], v[18:19]
	v_pk_add_f32 v[12:13], v[12:13], v[28:29]
	v_pk_add_f32 v[10:11], v[10:11], v[20:21]
	v_pk_add_f32 v[6:7], v[6:7], v[22:23]
	v_pk_add_f32 v[4:5], v[4:5], v[32:33]
	v_pk_add_f32 v[8:9], v[8:9], v[30:31]
	v_pk_add_f32 v[18:19], v[2:3], v[24:25]
	v_pk_add_f32 v[20:21], v[0:1], v[34:35]
	v_cvt_pk_bf16_f32 v0, v12, v13
	v_cvt_pk_bf16_f32 v1, v14, v15
	v_pk_mul_f32 v[2:3], v[14:15], v[14:15]
	v_pk_mul_f32 v[12:13], v[12:13], v[12:13]
	v_pk_mul_f32 v[14:15], v[10:11], v[10:11]
	v_pk_mul_f32 v[24:25], v[6:7], v[6:7]
	v_pk_mul_f32 v[28:29], v[4:5], v[4:5]
	v_pk_mul_f32 v[22:23], v[8:9], v[8:9]
	v_pk_mul_f32 v[32:33], v[20:21], v[20:21]
	v_add_f32_e32 v12, v12, v13
	v_add_f32_e32 v2, v2, v3
	v_add_f32_e32 v13, v14, v15
	v_add_f32_e32 v14, v28, v29
	v_add_f32_e32 v15, v24, v25
	v_pk_mul_f32 v[30:31], v[18:19], v[18:19]
	v_add_f32_e32 v3, v22, v23
	v_add_f32_e32 v22, v32, v33
	v_add_f32_e32 v2, v12, v2
	v_add_f32_e32 v12, v14, v15
	v_add_f32_e32 v23, v30, v31
	v_add_f32_e32 v2, v3, v2
	v_add_f32_e32 v3, v22, v12
	v_add_f32_e32 v2, v13, v2
	v_add_f32_e32 v3, v23, v3
	v_add_f32_e32 v12, v2, v3
	ds_bpermute_b32 v13, v157, v12
	v_cvt_pk_bf16_f32 v2, v8, v9
	v_cvt_pk_bf16_f32 v3, v10, v11
	global_store_dwordx4 v[26:27], v[0:3], off
	s_waitcnt lgkmcnt(0)
	s_nop 0
	v_add_f32_e32 v0, v12, v13
	ds_bpermute_b32 v1, v156, v0
	v_cvt_pk_bf16_f32 v2, v4, v5
	v_cvt_pk_bf16_f32 v3, v6, v7
	v_cvt_pk_bf16_f32 v4, v20, v21
	v_cvt_pk_bf16_f32 v5, v18, v19
	global_store_dwordx4 v[26:27], v[2:5], off offset:256
	s_and_saveexec_b64 s[6:7], s[2:3]
	s_cbranch_execz .LBB0_786
	s_waitcnt lgkmcnt(0)
	v_add_f32_e32 v0, v0, v1
	v_mul_f32_e32 v0, 0x4f800000, v0
	v_trunc_f32_e32 v0, v0
	v_mul_f32_e32 v1, 0x2f800000, v0
	v_floor_f32_e32 v1, v1
	v_fmac_f32_e32 v0, 0xcf800000, v1
	v_cvt_u32_f32_e32 v0, v0
	v_cvt_u32_f32_e32 v1, v1
	v_lshl_add_u64 v[2:3], v[16:17], 3, s[12:13]
	global_atomic_add_x2 v[2:3], v[0:1], off

; #define LAS __attribute__((address_space(3)))
; #define RUN(k) if ((k) != 10 && lo <= (k) && (k) < hi) { run_phase<PHM, (k)>(a0, lds0, a0.dry); if ((k) + 1 < hi) { if ((k) == 0) grid.sync(); else xcd_barrier(xbar); } }
; template <int PHM> __global__ void __launch_bounds__(512) fwd_kernel(Args a0) {
;     extern __shared__ __attribute__((aligned(16))) unsigned char lds_raw[];
;     LAS unsigned char* lds0 = (LAS unsigned char*)lds_raw;
;     cg::grid_group grid = cg::this_grid();
;     const int lo = a0.lo, hi = a0.hi;
;     if (threadIdx.x < 2) ((LAS unsigned*)(lds0 + LDS_BARW))[threadIdx.x] = 0u;
;     __syncthreads();
;     XcdBarrier xbar; xbar.bar = (unsigned*)(a0.ws + WS_BAR); xbar.x = 0; xbar.st = (volatile LAS unsigned*)(lds0 + LDS_BARW);
;     if (hi - lo > 1) xbar = xcd_barrier_post((unsigned*)(a0.ws + WS_BAR), (volatile LAS unsigned*)(lds0 + LDS_BARW));
;     ...
;     RUN(0) RUN(1) RUN(2) RUN(3) RUN(4) RUN(5) RUN(6) RUN(7) RUN(8) RUN(9) RUN(10)
;     RUN(11) RUN(12) RUN(13) RUN(14) RUN(15) RUN(16) RUN(17) RUN(18) RUN(19) RUN(20)
;     ...
; }
	.amdhsa_kernel _Z10fwd_kernelILi511EEv4Args
		.amdhsa_group_segment_fixed_size 0
		.amdhsa_private_segment_fixed_size 0
		.amdhsa_kernarg_size 456
		.amdhsa_user_sgpr_count 2
		.amdhsa_user_sgpr_dispatch_ptr 0
		.amdhsa_user_sgpr_queue_ptr 0
		.amdhsa_user_sgpr_kernarg_segment_ptr 1
		.amdhsa_user_sgpr_dispatch_id 0
		.amdhsa_user_sgpr_kernarg_preload_length 0
		.amdhsa_user_sgpr_kernarg_preload_offset 0
		.amdhsa_user_sgpr_private_segment_size 0
		.amdhsa_uses_dynamic_stack 0
		.amdhsa_enable_private_segment 0
		.amdhsa_system_sgpr_workgroup_id_x 1
		.amdhsa_system_sgpr_workgroup_id_y 0
		.amdhsa_system_sgpr_workgroup_id_z 0
		.amdhsa_system_sgpr_workgroup_info 0
		.amdhsa_system_vgpr_workitem_id 2
		.amdhsa_next_free_vgpr 239
		.amdhsa_next_free_sgpr 102
		.amdhsa_accum_offset 240
		.amdhsa_reserve_vcc 1
		.amdhsa_float_round_mode_32 0
		.amdhsa_float_round_mode_16_64 0
		.amdhsa_float_denorm_mode_32 3
		.amdhsa_float_denorm_mode_16_64 3
		.amdhsa_dx10_clamp 1
		.amdhsa_ieee_mode 1
		.amdhsa_fp16_overflow 0
		.amdhsa_tg_split 0
		.amdhsa_exception_fp_ieee_invalid_op 0
		.amdhsa_exception_fp_denorm_src 0
		.amdhsa_exception_fp_ieee_div_zero 0
		.amdhsa_exception_fp_ieee_overflow 0
		.amdhsa_exception_fp_ieee_underflow 0
		.amdhsa_exception_fp_ieee_inexact 0
		.amdhsa_exception_int_div_zero 0
	.end_amdhsa_kernel

; #define LAS __attribute__((address_space(3)))
; #define RUN(k) if ((k) != 10 && lo <= (k) && (k) < hi) { run_phase<PHM, (k)>(a0, lds0, a0.dry); if ((k) + 1 < hi) { if ((k) == 0) grid.sync(); else xcd_barrier(xbar); } }
; template <int PHM> __global__ void __launch_bounds__(512) fwd_kernel(Args a0) {
;     extern __shared__ __attribute__((aligned(16))) unsigned char lds_raw[];
;     LAS unsigned char* lds0 = (LAS unsigned char*)lds_raw;
;     cg::grid_group grid = cg::this_grid();
;     const int lo = a0.lo, hi = a0.hi;
;     if (threadIdx.x < 2) ((LAS unsigned*)(lds0 + LDS_BARW))[threadIdx.x] = 0u;
;     __syncthreads();
;     XcdBarrier xbar; xbar.bar = (unsigned*)(a0.ws + WS_BAR); xbar.x = 0; xbar.st = (volatile LAS unsigned*)(lds0 + LDS_BARW);
;     if (hi - lo > 1) xbar = xcd_barrier_post((unsigned*)(a0.ws + WS_BAR), (volatile LAS unsigned*)(lds0 + LDS_BARW));
;     ...
;     RUN(0) RUN(1) RUN(2) RUN(3) RUN(4) RUN(5) RUN(6) RUN(7) RUN(8) RUN(9) RUN(10)
;     RUN(11) RUN(12) RUN(13) RUN(14) RUN(15) RUN(16) RUN(17) RUN(18) RUN(19) RUN(20)
;     ...
; }
amdhsa.kernels:
  - .agpr_count:     0
    .args:
      - .offset:         0
        .size:           200
        .value_kind:     by_value
      - .offset:         200
        .size:           4
        .value_kind:     hidden_block_count_x
      - .offset:         204
        .size:           4
        .value_kind:     hidden_block_count_y
      - .offset:         208
        .size:           4
        .value_kind:     hidden_block_count_z
      - .offset:         212
        .size:           2
        .value_kind:     hidden_group_size_x
      - .offset:         214
        .size:           2
        .value_kind:     hidden_group_size_y
      - .offset:         216
        .size:           2
        .value_kind:     hidden_group_size_z
      - .offset:         218
        .size:           2
        .value_kind:     hidden_remainder_x
      - .offset:         220
        .size:           2
        .value_kind:     hidden_remainder_y
      - .offset:         222
        .size:           2
        .value_kind:     hidden_remainder_z
      - .offset:         240
        .size:           8
        .value_kind:     hidden_global_offset_x
      - .offset:         248
        .size:           8
        .value_kind:     hidden_global_offset_y
      - .offset:         256
        .size:           8
        .value_kind:     hidden_global_offset_z
      - .offset:         264
        .size:           2
        .value_kind:     hidden_grid_dims
      - .offset:         288
        .size:           8
        .value_kind:     hidden_multigrid_sync_arg
      - .offset:         320
        .size:           4
        .value_kind:     hidden_dynamic_lds_size
    .group_segment_fixed_size: 0
    .kernarg_segment_align: 8
    .kernarg_segment_size: 456
    .language:       OpenCL C
    .language_version:
      - 2
      - 0
    .max_flat_workgroup_size: 512
    .name:           _Z10fwd_kernelILi511EEv4Args
    .private_segment_fixed_size: 0
    .sgpr_count:     108
    .sgpr_spill_count: 24
    .symbol:         _Z10fwd_kernelILi511EEv4Args.kd
    .uniform_work_group_size: 1
    .uses_dynamic_stack: false
    .vgpr_count:     239
    .vgpr_spill_count: 0
    .wavefront_size: 64
